# handwritten-pool-unit-ldsdma-sliding-window
# speedup vs baseline: 1.0521x; 1.0229x over previous
.LBB0_80:
	s_movk_i32 s34, 0x2ff
	v_writelane_b32 v250, s40, 37
	v_cmp_lt_u32_e32 vcc, s34, v2
	s_nop 0
	v_writelane_b32 v250, s41, 38
	s_and_saveexec_b64 s[38:39], vcc
	s_xor_b64 s[38:39], exec, s[38:39]
	s_cbranch_execz .LBB0_170
	v_writelane_b32 v250, s38, 39
	v_and_b32_e32 v0, 63, v128
	v_writelane_b32 v250, s39, 40
	v_readfirstlane_b32 s40, v2
	v_readfirstlane_b32 s41, v128
	s_mov_b32 s59, m0
	s_sub_i32 s40, s40, 0x300
	s_lshl_b32 s40, s40, 8
	s_lshr_b32 s41, s41, 6
	s_and_b32 s42, s40, 0xfff
	s_or_b32 s42, s42, s41
	s_cmp_eq_u32 s42, 0
	s_cselect_b32 s42, 1, 0
	v_lshrrev_b32_e32 v2, 4, v0
	v_and_b32_e32 v3, 15, v0
	v_lshlrev_b32_e32 v2, 9, v2
	v_lshl_or_b32 v6, v3, 4, v2
	v_mov_b32_e32 v7, 0
	s_lshl_b32 s43, s41, 13
	v_lshl_add_u32 v8, v0, 1, s43
	s_mul_i32 s43, s41, 0x1200
	s_add_i32 s43, s43, 0x11000
	v_lshl_add_u32 v9, v0, 1, s43
	v_and_b32_e32 v2, 31, v0
	v_lshrrev_b32_e32 v3, 5, v0
	v_mul_u32_u24_e32 v44, 0x90, v2
	v_lshl_add_u32 v44, v3, 4, v44
	v_add_u32_e32 v44, s43, v44
	s_lshl_b32 s43, s41, 16
	v_lshlrev_b32_e32 v10, 11, v2
	v_lshl_add_u32 v10, v3, 3, v10
	s_addk_i32 s43, 0x400
	v_add_u32_e32 v10, s43, v10
	v_mov_b32_e32 v11, 0
	v_lshlrev_b32_e32 v45, 7, v2
	v_lshl_add_u32 v45, v3, 4, v45
	v_add_u32_e32 v45, 0x800, v45
	s_lshl_b32 s43, s40, 11
	s_add_u32 s52, s70, 0x95c8000
	s_addc_u32 s53, s71, 0
	s_add_u32 s52, s52, s43
	s_addc_u32 s53, s53, 0
	s_sub_i32 s43, s40, 15
	s_lshl_b32 s43, s43, 9
	s_ashr_i32 s49, s43, 31
	s_add_u32 s44, s70, 0x7548000
	s_addc_u32 s45, s71, 0
	s_add_u32 s44, s44, s43
	s_addc_u32 s45, s45, s49
	s_lshl_b32 s43, s41, 11
	s_add_u32 s44, s44, s43
	s_addc_u32 s45, s45, 0
	s_lshl_b32 s48, s41, 10
	s_barrier
	s_add_u32 s46, s44, 0x0
	s_addc_u32 s47, s45, 0
	s_add_i32 s43, s48, 0x0
	v_lshl_add_u64 v[4:5], s[46:47], 0, v[6:7]
	s_mov_b32 m0, s43
	s_nop 0
	global_load_lds_dwordx4 v[4:5], off
	s_add_u32 s46, s44, 0x4000
	s_addc_u32 s47, s45, 0
	s_add_i32 s43, s48, 0x2000
	v_lshl_add_u64 v[4:5], s[46:47], 0, v[6:7]
	s_mov_b32 m0, s43
	s_nop 0
	global_load_lds_dwordx4 v[4:5], off
	s_add_u32 s46, s44, 0x8000
	s_addc_u32 s47, s45, 0
	s_add_i32 s43, s48, 0x4000
	v_lshl_add_u64 v[4:5], s[46:47], 0, v[6:7]
	s_mov_b32 m0, s43
	s_nop 0
	global_load_lds_dwordx4 v[4:5], off
	s_add_u32 s46, s44, 0xc000
	s_addc_u32 s47, s45, 0
	s_add_i32 s43, s48, 0x6000
	v_lshl_add_u64 v[4:5], s[46:47], 0, v[6:7]
	s_mov_b32 m0, s43
	s_nop 0
	global_load_lds_dwordx4 v[4:5], off
	s_add_u32 s46, s44, 0x10000
	s_addc_u32 s47, s45, 0
	s_add_i32 s43, s48, 0x8000
	v_lshl_add_u64 v[4:5], s[46:47], 0, v[6:7]
	s_mov_b32 m0, s43
	s_nop 0
	global_load_lds_dwordx4 v[4:5], off
	s_add_u32 s46, s44, 0x14000
	s_addc_u32 s47, s45, 0
	s_add_i32 s43, s48, 0xa000
	v_lshl_add_u64 v[4:5], s[46:47], 0, v[6:7]
	s_mov_b32 m0, s43
	s_nop 0
	global_load_lds_dwordx4 v[4:5], off
	s_add_u32 s46, s44, 0x18000
	s_addc_u32 s47, s45, 0
	s_add_i32 s43, s48, 0xc000
	v_lshl_add_u64 v[4:5], s[46:47], 0, v[6:7]
	s_mov_b32 m0, s43
	s_nop 0
	global_load_lds_dwordx4 v[4:5], off
	s_add_u32 s46, s44, 0x1c000
	s_addc_u32 s47, s45, 0
	s_add_i32 s43, s48, 0xe000
	v_lshl_add_u64 v[4:5], s[46:47], 0, v[6:7]
	s_mov_b32 m0, s43
	s_nop 0
	global_load_lds_dwordx4 v[4:5], off
	s_cmp_lt_u32 s41, 4
	s_cbranch_scc0 .Lpool_dma_done0
	s_add_u32 s46, s44, 0x20000
	s_addc_u32 s47, s45, 0
	s_add_i32 s43, s48, 0x10000
	v_lshl_add_u64 v[4:5], s[46:47], 0, v[6:7]
	s_mov_b32 m0, s43
	s_nop 0
	global_load_lds_dwordx4 v[4:5], off
.Lpool_dma_done0:
	s_waitcnt vmcnt(0)
	s_barrier
	v_readlane_b32 s54, v250, 23
	v_readlane_b32 s55, v250, 24
	v_mov_b32_e32 v2, v45
	v_mov_b32_e32 v3, 0
	s_nop 1
	v_lshl_add_u64 v[4:5], s[54:55], 0, v[2:3]
	global_load_dwordx4 v[12:15], v[4:5], off offset:-2048
	global_load_dwordx4 v[16:19], v[4:5], off offset:2048
	global_load_dwordx4 v[20:23], v[4:5], off offset:-2016
	global_load_dwordx4 v[24:27], v[4:5], off offset:2080
	global_load_dwordx4 v[28:31], v[4:5], off offset:-1984
	global_load_dwordx4 v[32:35], v[4:5], off offset:2112
	global_load_dwordx4 v[36:39], v[4:5], off offset:-1952
	global_load_dwordx4 v[40:43], v[4:5], off offset:2144
	ds_read_u16 v60, v8 offset:3584
	ds_read_u16 v61, v8 offset:3840
	ds_read_u16 v62, v8 offset:4096
	ds_read_u16 v63, v8 offset:4352
	ds_read_u16 v64, v8 offset:4608
	ds_read_u16 v65, v8 offset:4864
	ds_read_u16 v66, v8 offset:5120
	ds_read_u16 v67, v8 offset:5376
	ds_read_u16 v68, v8 offset:5632
	ds_read_u16 v69, v8 offset:5888
	ds_read_u16 v70, v8 offset:6144
	ds_read_u16 v71, v8 offset:6400
	ds_read_u16 v72, v8 offset:6656
	ds_read_u16 v73, v8 offset:6912
	ds_read_u16 v74, v8 offset:7168
	ds_read_u16 v75, v8 offset:7424
	ds_read_u16 v76, v8 offset:7680
	ds_read_u16 v77, v8 offset:7936
	ds_read_u16 v78, v8 offset:8192
	ds_read_u16 v79, v8 offset:8448
	ds_read_u16 v80, v8 offset:8704
	ds_read_u16 v81, v8 offset:8960
	ds_read_u16 v82, v8 offset:9216
	ds_read_u16 v83, v8 offset:9472
	ds_read_u16 v84, v8 offset:9728
	ds_read_u16 v85, v8 offset:9984
	ds_read_u16 v86, v8 offset:10240
	ds_read_u16 v87, v8 offset:10496
	ds_read_u16 v88, v8 offset:10752
	ds_read_u16 v89, v8 offset:11008
	ds_read_u16 v90, v8 offset:11264
	ds_read_u16 v91, v8 offset:11520
	ds_read_u16 v92, v8 offset:11776
	s_mov_b32 s50, 0x3f000000
	s_waitcnt lgkmcnt(0)
	v_lshlrev_b32_e32 v60, 16, v60
	v_lshlrev_b32_e32 v61, 16, v61
	v_lshlrev_b32_e32 v62, 16, v62
	v_lshlrev_b32_e32 v63, 16, v63
	v_lshlrev_b32_e32 v64, 16, v64
	v_lshlrev_b32_e32 v65, 16, v65
	v_lshlrev_b32_e32 v66, 16, v66
	v_lshlrev_b32_e32 v67, 16, v67
	v_lshlrev_b32_e32 v68, 16, v68
	v_lshlrev_b32_e32 v69, 16, v69
	v_lshlrev_b32_e32 v70, 16, v70
	v_lshlrev_b32_e32 v71, 16, v71
	v_lshlrev_b32_e32 v72, 16, v72
	v_lshlrev_b32_e32 v73, 16, v73
	v_lshlrev_b32_e32 v74, 16, v74
	v_lshlrev_b32_e32 v75, 16, v75
	v_lshlrev_b32_e32 v76, 16, v76
	v_lshlrev_b32_e32 v77, 16, v77
	v_lshlrev_b32_e32 v78, 16, v78
	v_lshlrev_b32_e32 v79, 16, v79
	v_lshlrev_b32_e32 v80, 16, v80
	v_lshlrev_b32_e32 v81, 16, v81
	v_lshlrev_b32_e32 v82, 16, v82
	v_lshlrev_b32_e32 v83, 16, v83
	v_lshlrev_b32_e32 v84, 16, v84
	v_lshlrev_b32_e32 v85, 16, v85
	v_lshlrev_b32_e32 v86, 16, v86
	v_lshlrev_b32_e32 v87, 16, v87
	v_lshlrev_b32_e32 v88, 16, v88
	v_lshlrev_b32_e32 v89, 16, v89
	v_lshlrev_b32_e32 v90, 16, v90
	v_lshlrev_b32_e32 v91, 16, v91
	v_lshlrev_b32_e32 v92, 16, v92
	s_cmp_eq_u32 s42, 1
	s_cbranch_scc0 .Lpool_nz0
	v_mov_b32_e32 v60, 0
.Lpool_nz0:
	v_add_f32_e32 v93, v61, v60
	s_cmp_eq_u32 s42, 1
	s_cselect_b32 s51, 0x3f800000, s50
	v_fma_f32 v2, v93, s51, -v61
	v_add_f32_e32 v93, v93, v62
	v_sub_f32_e32 v93, v93, v60
	v_fma_f32 v3, v93, s50, -v62
	v_cvt_pk_bf16_f32 v2, v2, v3
	ds_write_b16 v9, v2 offset:0
	ds_write_b16_d16_hi v9, v2 offset:144
	v_add_f32_e32 v93, v93, v63
	v_sub_f32_e32 v93, v93, v61
	v_fma_f32 v4, v93, s50, -v63
	v_add_f32_e32 v93, v93, v64
	v_sub_f32_e32 v93, v93, v62
	v_fma_f32 v5, v93, s50, -v64
	v_cvt_pk_bf16_f32 v4, v4, v5
	ds_write_b16 v9, v4 offset:288
	ds_write_b16_d16_hi v9, v4 offset:432
	v_add_f32_e32 v93, v93, v65
	v_sub_f32_e32 v93, v93, v63
	v_fma_f32 v2, v93, s50, -v65
	v_add_f32_e32 v93, v93, v66
	v_sub_f32_e32 v93, v93, v64
	v_fma_f32 v3, v93, s50, -v66
	v_cvt_pk_bf16_f32 v2, v2, v3
	ds_write_b16 v9, v2 offset:576
	ds_write_b16_d16_hi v9, v2 offset:720
	v_add_f32_e32 v93, v93, v67
	v_sub_f32_e32 v93, v93, v65
	v_fma_f32 v4, v93, s50, -v67
	v_add_f32_e32 v93, v93, v68
	v_sub_f32_e32 v93, v93, v66
	v_fma_f32 v5, v93, s50, -v68
	v_cvt_pk_bf16_f32 v4, v4, v5
	ds_write_b16 v9, v4 offset:864
	ds_write_b16_d16_hi v9, v4 offset:1008
	v_add_f32_e32 v93, v93, v69
	v_sub_f32_e32 v93, v93, v67
	v_fma_f32 v2, v93, s50, -v69
	v_add_f32_e32 v93, v93, v70
	v_sub_f32_e32 v93, v93, v68
	v_fma_f32 v3, v93, s50, -v70
	v_cvt_pk_bf16_f32 v2, v2, v3
	ds_write_b16 v9, v2 offset:1152
	ds_write_b16_d16_hi v9, v2 offset:1296
	v_add_f32_e32 v93, v93, v71
	v_sub_f32_e32 v93, v93, v69
	v_fma_f32 v4, v93, s50, -v71
	v_add_f32_e32 v93, v93, v72
	v_sub_f32_e32 v93, v93, v70
	v_fma_f32 v5, v93, s50, -v72
	v_cvt_pk_bf16_f32 v4, v4, v5
	ds_write_b16 v9, v4 offset:1440
	ds_write_b16_d16_hi v9, v4 offset:1584
	v_add_f32_e32 v93, v93, v73
	v_sub_f32_e32 v93, v93, v71
	v_fma_f32 v2, v93, s50, -v73
	v_add_f32_e32 v93, v93, v74
	v_sub_f32_e32 v93, v93, v72
	v_fma_f32 v3, v93, s50, -v74
	v_cvt_pk_bf16_f32 v2, v2, v3
	ds_write_b16 v9, v2 offset:1728
	ds_write_b16_d16_hi v9, v2 offset:1872
	v_add_f32_e32 v93, v93, v75
	v_sub_f32_e32 v93, v93, v73
	v_fma_f32 v4, v93, s50, -v75
	v_add_f32_e32 v93, v93, v76
	v_sub_f32_e32 v93, v93, v74
	v_fma_f32 v5, v93, s50, -v76
	v_cvt_pk_bf16_f32 v4, v4, v5
	ds_write_b16 v9, v4 offset:2016
	ds_write_b16_d16_hi v9, v4 offset:2160
	v_add_f32_e32 v93, v93, v77
	v_sub_f32_e32 v93, v93, v75
	v_fma_f32 v2, v93, s50, -v77
	v_add_f32_e32 v93, v93, v78
	v_sub_f32_e32 v93, v93, v76
	v_fma_f32 v3, v93, s50, -v78
	v_cvt_pk_bf16_f32 v2, v2, v3
	ds_write_b16 v9, v2 offset:2304
	ds_write_b16_d16_hi v9, v2 offset:2448
	v_add_f32_e32 v93, v93, v79
	v_sub_f32_e32 v93, v93, v77
	v_fma_f32 v4, v93, s50, -v79
	v_add_f32_e32 v93, v93, v80
	v_sub_f32_e32 v93, v93, v78
	v_fma_f32 v5, v93, s50, -v80
	v_cvt_pk_bf16_f32 v4, v4, v5
	ds_write_b16 v9, v4 offset:2592
	ds_write_b16_d16_hi v9, v4 offset:2736
	v_add_f32_e32 v93, v93, v81
	v_sub_f32_e32 v93, v93, v79
	v_fma_f32 v2, v93, s50, -v81
	v_add_f32_e32 v93, v93, v82
	v_sub_f32_e32 v93, v93, v80
	v_fma_f32 v3, v93, s50, -v82
	v_cvt_pk_bf16_f32 v2, v2, v3
	ds_write_b16 v9, v2 offset:2880
	ds_write_b16_d16_hi v9, v2 offset:3024
	v_add_f32_e32 v93, v93, v83
	v_sub_f32_e32 v93, v93, v81
	v_fma_f32 v4, v93, s50, -v83
	v_add_f32_e32 v93, v93, v84
	v_sub_f32_e32 v93, v93, v82
	v_fma_f32 v5, v93, s50, -v84
	v_cvt_pk_bf16_f32 v4, v4, v5
	ds_write_b16 v9, v4 offset:3168
	ds_write_b16_d16_hi v9, v4 offset:3312
	v_add_f32_e32 v93, v93, v85
	v_sub_f32_e32 v93, v93, v83
	v_fma_f32 v2, v93, s50, -v85
	v_add_f32_e32 v93, v93, v86
	v_sub_f32_e32 v93, v93, v84
	v_fma_f32 v3, v93, s50, -v86
	v_cvt_pk_bf16_f32 v2, v2, v3
	ds_write_b16 v9, v2 offset:3456
	ds_write_b16_d16_hi v9, v2 offset:3600
	v_add_f32_e32 v93, v93, v87
	v_sub_f32_e32 v93, v93, v85
	v_fma_f32 v4, v93, s50, -v87
	v_add_f32_e32 v93, v93, v88
	v_sub_f32_e32 v93, v93, v86
	v_fma_f32 v5, v93, s50, -v88
	v_cvt_pk_bf16_f32 v4, v4, v5
	ds_write_b16 v9, v4 offset:3744
	ds_write_b16_d16_hi v9, v4 offset:3888
	v_add_f32_e32 v93, v93, v89
	v_sub_f32_e32 v93, v93, v87
	v_fma_f32 v2, v93, s50, -v89
	v_add_f32_e32 v93, v93, v90
	v_sub_f32_e32 v93, v93, v88
	v_fma_f32 v3, v93, s50, -v90
	v_cvt_pk_bf16_f32 v2, v2, v3
	ds_write_b16 v9, v2 offset:4032
	ds_write_b16_d16_hi v9, v2 offset:4176
	v_add_f32_e32 v93, v93, v91
	v_sub_f32_e32 v93, v93, v89
	v_fma_f32 v4, v93, s50, -v91
	v_add_f32_e32 v93, v93, v92
	v_sub_f32_e32 v93, v93, v90
	v_fma_f32 v5, v93, s50, -v92
	v_cvt_pk_bf16_f32 v4, v4, v5
	ds_write_b16 v9, v4 offset:4320
	ds_write_b16_d16_hi v9, v4 offset:4464
	s_waitcnt lgkmcnt(0)
	ds_read_b128 v[78:81], v44 offset:0
	ds_read_b128 v[82:85], v44 offset:32
	ds_read_b128 v[86:89], v44 offset:64
	ds_read_b128 v[90:93], v44 offset:96
	v_lshl_add_u64 v[4:5], s[52:53], 0, v[10:11]
	s_waitcnt vmcnt(0)
	s_waitcnt lgkmcnt(0)
	v_mfma_f32_32x32x16_bf16 v[46:61], v[12:15], v[78:81], 0
	v_mfma_f32_32x32x16_bf16 v[62:77], v[16:19], v[78:81], 0
	global_load_dwordx2 v[12:13], v[4:5], off offset:0
	global_load_dwordx2 v[14:15], v[4:5], off offset:16
	global_load_dwordx2 v[16:17], v[4:5], off offset:32
	global_load_dwordx2 v[18:19], v[4:5], off offset:48
	v_mfma_f32_32x32x16_bf16 v[46:61], v[20:23], v[82:85], v[46:61]
	v_mfma_f32_32x32x16_bf16 v[62:77], v[24:27], v[82:85], v[62:77]
	global_load_dwordx2 v[20:21], v[4:5], off offset:64
	global_load_dwordx2 v[22:23], v[4:5], off offset:80
	global_load_dwordx2 v[24:25], v[4:5], off offset:96
	global_load_dwordx2 v[26:27], v[4:5], off offset:112
	v_mfma_f32_32x32x16_bf16 v[46:61], v[28:31], v[86:89], v[46:61]
	v_mfma_f32_32x32x16_bf16 v[62:77], v[32:35], v[86:89], v[62:77]
	v_mfma_f32_32x32x16_bf16 v[46:61], v[36:39], v[90:93], v[46:61]
	v_mfma_f32_32x32x16_bf16 v[62:77], v[40:43], v[90:93], v[62:77]
	s_nop 15
	s_waitcnt vmcnt(0)
	v_lshlrev_b32_e32 v32, 16, v12
	v_and_b32_e32 v33, 0xffff0000, v12
	v_lshlrev_b32_e32 v34, 16, v13
	v_and_b32_e32 v35, 0xffff0000, v13
	v_mul_f32_e32 v28, 0xbfb8aa3b, v32
	v_mul_f32_e32 v29, 0xbfb8aa3b, v33
	v_mul_f32_e32 v30, 0xbfb8aa3b, v34
	v_mul_f32_e32 v31, 0xbfb8aa3b, v35
	v_exp_f32_e32 v28, v28
	v_exp_f32_e32 v29, v29
	v_exp_f32_e32 v30, v30
	v_exp_f32_e32 v31, v31
	v_add_f32_e32 v28, 1.0, v28
	v_add_f32_e32 v29, 1.0, v29
	v_add_f32_e32 v30, 1.0, v30
	v_add_f32_e32 v31, 1.0, v31
	v_rcp_f32_e32 v28, v28
	v_rcp_f32_e32 v29, v29
	v_rcp_f32_e32 v30, v30
	v_rcp_f32_e32 v31, v31
	v_pk_mul_f32 v[28:29], v[32:33], v[28:29]
	v_pk_mul_f32 v[30:31], v[34:35], v[30:31]
	v_pk_mul_f32 v[28:29], v[46:47], v[28:29]
	v_pk_mul_f32 v[30:31], v[48:49], v[30:31]
	v_cvt_pk_bf16_f32 v36, v28, v29
	v_cvt_pk_bf16_f32 v37, v30, v31
	global_store_dwordx2 v[4:5], v[36:37], off offset:0
	v_lshlrev_b32_e32 v32, 16, v14
	v_and_b32_e32 v33, 0xffff0000, v14
	v_lshlrev_b32_e32 v34, 16, v15
	v_and_b32_e32 v35, 0xffff0000, v15
	v_mul_f32_e32 v28, 0xbfb8aa3b, v32
	v_mul_f32_e32 v29, 0xbfb8aa3b, v33
	v_mul_f32_e32 v30, 0xbfb8aa3b, v34
	v_mul_f32_e32 v31, 0xbfb8aa3b, v35
	v_exp_f32_e32 v28, v28
	v_exp_f32_e32 v29, v29
	v_exp_f32_e32 v30, v30
	v_exp_f32_e32 v31, v31
	v_add_f32_e32 v28, 1.0, v28
	v_add_f32_e32 v29, 1.0, v29
	v_add_f32_e32 v30, 1.0, v30
	v_add_f32_e32 v31, 1.0, v31
	v_rcp_f32_e32 v28, v28
	v_rcp_f32_e32 v29, v29
	v_rcp_f32_e32 v30, v30
	v_rcp_f32_e32 v31, v31
	v_pk_mul_f32 v[28:29], v[32:33], v[28:29]
	v_pk_mul_f32 v[30:31], v[34:35], v[30:31]
	v_pk_mul_f32 v[28:29], v[50:51], v[28:29]
	v_pk_mul_f32 v[30:31], v[52:53], v[30:31]
	v_cvt_pk_bf16_f32 v38, v28, v29
	v_cvt_pk_bf16_f32 v39, v30, v31
	global_store_dwordx2 v[4:5], v[38:39], off offset:16
	v_lshlrev_b32_e32 v32, 16, v16
	v_and_b32_e32 v33, 0xffff0000, v16
	v_lshlrev_b32_e32 v34, 16, v17
	v_and_b32_e32 v35, 0xffff0000, v17
	v_mul_f32_e32 v28, 0xbfb8aa3b, v32
	v_mul_f32_e32 v29, 0xbfb8aa3b, v33
	v_mul_f32_e32 v30, 0xbfb8aa3b, v34
	v_mul_f32_e32 v31, 0xbfb8aa3b, v35
	v_exp_f32_e32 v28, v28
	v_exp_f32_e32 v29, v29
	v_exp_f32_e32 v30, v30
	v_exp_f32_e32 v31, v31
	v_add_f32_e32 v28, 1.0, v28
	v_add_f32_e32 v29, 1.0, v29
	v_add_f32_e32 v30, 1.0, v30
	v_add_f32_e32 v31, 1.0, v31
	v_rcp_f32_e32 v28, v28
	v_rcp_f32_e32 v29, v29
	v_rcp_f32_e32 v30, v30
	v_rcp_f32_e32 v31, v31
	v_pk_mul_f32 v[28:29], v[32:33], v[28:29]
	v_pk_mul_f32 v[30:31], v[34:35], v[30:31]
	v_pk_mul_f32 v[28:29], v[54:55], v[28:29]
	v_pk_mul_f32 v[30:31], v[56:57], v[30:31]
	v_cvt_pk_bf16_f32 v36, v28, v29
	v_cvt_pk_bf16_f32 v37, v30, v31
	global_store_dwordx2 v[4:5], v[36:37], off offset:32
	v_lshlrev_b32_e32 v32, 16, v18
	v_and_b32_e32 v33, 0xffff0000, v18
	v_lshlrev_b32_e32 v34, 16, v19
	v_and_b32_e32 v35, 0xffff0000, v19
	v_mul_f32_e32 v28, 0xbfb8aa3b, v32
	v_mul_f32_e32 v29, 0xbfb8aa3b, v33
	v_mul_f32_e32 v30, 0xbfb8aa3b, v34
	v_mul_f32_e32 v31, 0xbfb8aa3b, v35
	v_exp_f32_e32 v28, v28
	v_exp_f32_e32 v29, v29
	v_exp_f32_e32 v30, v30
	v_exp_f32_e32 v31, v31
	v_add_f32_e32 v28, 1.0, v28
	v_add_f32_e32 v29, 1.0, v29
	v_add_f32_e32 v30, 1.0, v30
	v_add_f32_e32 v31, 1.0, v31
	v_rcp_f32_e32 v28, v28
	v_rcp_f32_e32 v29, v29
	v_rcp_f32_e32 v30, v30
	v_rcp_f32_e32 v31, v31
	v_pk_mul_f32 v[28:29], v[32:33], v[28:29]
	v_pk_mul_f32 v[30:31], v[34:35], v[30:31]
	v_pk_mul_f32 v[28:29], v[58:59], v[28:29]
	v_pk_mul_f32 v[30:31], v[60:61], v[30:31]
	v_cvt_pk_bf16_f32 v38, v28, v29
	v_cvt_pk_bf16_f32 v39, v30, v31
	global_store_dwordx2 v[4:5], v[38:39], off offset:48
	v_lshlrev_b32_e32 v32, 16, v20
	v_and_b32_e32 v33, 0xffff0000, v20
	v_lshlrev_b32_e32 v34, 16, v21
	v_and_b32_e32 v35, 0xffff0000, v21
	v_mul_f32_e32 v28, 0xbfb8aa3b, v32
	v_mul_f32_e32 v29, 0xbfb8aa3b, v33
	v_mul_f32_e32 v30, 0xbfb8aa3b, v34
	v_mul_f32_e32 v31, 0xbfb8aa3b, v35
	v_exp_f32_e32 v28, v28
	v_exp_f32_e32 v29, v29
	v_exp_f32_e32 v30, v30
	v_exp_f32_e32 v31, v31
	v_add_f32_e32 v28, 1.0, v28
	v_add_f32_e32 v29, 1.0, v29
	v_add_f32_e32 v30, 1.0, v30
	v_add_f32_e32 v31, 1.0, v31
	v_rcp_f32_e32 v28, v28
	v_rcp_f32_e32 v29, v29
	v_rcp_f32_e32 v30, v30
	v_rcp_f32_e32 v31, v31
	v_pk_mul_f32 v[28:29], v[32:33], v[28:29]
	v_pk_mul_f32 v[30:31], v[34:35], v[30:31]
	v_pk_mul_f32 v[28:29], v[62:63], v[28:29]
	v_pk_mul_f32 v[30:31], v[64:65], v[30:31]
	v_cvt_pk_bf16_f32 v36, v28, v29
	v_cvt_pk_bf16_f32 v37, v30, v31
	global_store_dwordx2 v[4:5], v[36:37], off offset:64
	v_lshlrev_b32_e32 v32, 16, v22
	v_and_b32_e32 v33, 0xffff0000, v22
	v_lshlrev_b32_e32 v34, 16, v23
	v_and_b32_e32 v35, 0xffff0000, v23
	v_mul_f32_e32 v28, 0xbfb8aa3b, v32
	v_mul_f32_e32 v29, 0xbfb8aa3b, v33
	v_mul_f32_e32 v30, 0xbfb8aa3b, v34
	v_mul_f32_e32 v31, 0xbfb8aa3b, v35
	v_exp_f32_e32 v28, v28
	v_exp_f32_e32 v29, v29
	v_exp_f32_e32 v30, v30
	v_exp_f32_e32 v31, v31
	v_add_f32_e32 v28, 1.0, v28
	v_add_f32_e32 v29, 1.0, v29
	v_add_f32_e32 v30, 1.0, v30
	v_add_f32_e32 v31, 1.0, v31
	v_rcp_f32_e32 v28, v28
	v_rcp_f32_e32 v29, v29
	v_rcp_f32_e32 v30, v30
	v_rcp_f32_e32 v31, v31
	v_pk_mul_f32 v[28:29], v[32:33], v[28:29]
	v_pk_mul_f32 v[30:31], v[34:35], v[30:31]
	v_pk_mul_f32 v[28:29], v[66:67], v[28:29]
	v_pk_mul_f32 v[30:31], v[68:69], v[30:31]
	v_cvt_pk_bf16_f32 v38, v28, v29
	v_cvt_pk_bf16_f32 v39, v30, v31
	global_store_dwordx2 v[4:5], v[38:39], off offset:80
	v_lshlrev_b32_e32 v32, 16, v24
	v_and_b32_e32 v33, 0xffff0000, v24
	v_lshlrev_b32_e32 v34, 16, v25
	v_and_b32_e32 v35, 0xffff0000, v25
	v_mul_f32_e32 v28, 0xbfb8aa3b, v32
	v_mul_f32_e32 v29, 0xbfb8aa3b, v33
	v_mul_f32_e32 v30, 0xbfb8aa3b, v34
	v_mul_f32_e32 v31, 0xbfb8aa3b, v35
	v_exp_f32_e32 v28, v28
	v_exp_f32_e32 v29, v29
	v_exp_f32_e32 v30, v30
	v_exp_f32_e32 v31, v31
	v_add_f32_e32 v28, 1.0, v28
	v_add_f32_e32 v29, 1.0, v29
	v_add_f32_e32 v30, 1.0, v30
	v_add_f32_e32 v31, 1.0, v31
	v_rcp_f32_e32 v28, v28
	v_rcp_f32_e32 v29, v29
	v_rcp_f32_e32 v30, v30
	v_rcp_f32_e32 v31, v31
	v_pk_mul_f32 v[28:29], v[32:33], v[28:29]
	v_pk_mul_f32 v[30:31], v[34:35], v[30:31]
	v_pk_mul_f32 v[28:29], v[70:71], v[28:29]
	v_pk_mul_f32 v[30:31], v[72:73], v[30:31]
	v_cvt_pk_bf16_f32 v36, v28, v29
	v_cvt_pk_bf16_f32 v37, v30, v31
	global_store_dwordx2 v[4:5], v[36:37], off offset:96
	v_lshlrev_b32_e32 v32, 16, v26
	v_and_b32_e32 v33, 0xffff0000, v26
	v_lshlrev_b32_e32 v34, 16, v27
	v_and_b32_e32 v35, 0xffff0000, v27
	v_mul_f32_e32 v28, 0xbfb8aa3b, v32
	v_mul_f32_e32 v29, 0xbfb8aa3b, v33
	v_mul_f32_e32 v30, 0xbfb8aa3b, v34
	v_mul_f32_e32 v31, 0xbfb8aa3b, v35
	v_exp_f32_e32 v28, v28
	v_exp_f32_e32 v29, v29
	v_exp_f32_e32 v30, v30
	v_exp_f32_e32 v31, v31
	v_add_f32_e32 v28, 1.0, v28
	v_add_f32_e32 v29, 1.0, v29
	v_add_f32_e32 v30, 1.0, v30
	v_add_f32_e32 v31, 1.0, v31
	v_rcp_f32_e32 v28, v28
	v_rcp_f32_e32 v29, v29
	v_rcp_f32_e32 v30, v30
	v_rcp_f32_e32 v31, v31
	v_pk_mul_f32 v[28:29], v[32:33], v[28:29]
	v_pk_mul_f32 v[30:31], v[34:35], v[30:31]
	v_pk_mul_f32 v[28:29], v[74:75], v[28:29]
	v_pk_mul_f32 v[30:31], v[76:77], v[30:31]
	v_cvt_pk_bf16_f32 v38, v28, v29
	v_cvt_pk_bf16_f32 v39, v30, v31
	global_store_dwordx2 v[4:5], v[38:39], off offset:112
	v_readlane_b32 s54, v250, 25
	v_readlane_b32 s55, v250, 26
	v_mov_b32_e32 v2, v45
	v_mov_b32_e32 v3, 0
	s_nop 1
	v_lshl_add_u64 v[4:5], s[54:55], 0, v[2:3]
	global_load_dwordx4 v[12:15], v[4:5], off offset:-2048
	global_load_dwordx4 v[16:19], v[4:5], off offset:2048
	global_load_dwordx4 v[20:23], v[4:5], off offset:-2016
	global_load_dwordx4 v[24:27], v[4:5], off offset:2080
	global_load_dwordx4 v[28:31], v[4:5], off offset:-1984
	global_load_dwordx4 v[32:35], v[4:5], off offset:2112
	global_load_dwordx4 v[36:39], v[4:5], off offset:-1952
	global_load_dwordx4 v[40:43], v[4:5], off offset:2144
	ds_read_u16 v58, v8 offset:3200
	ds_read_u16 v59, v8 offset:3456
	ds_read_u16 v60, v8 offset:3712
	ds_read_u16 v61, v8 offset:3968
	ds_read_u16 v62, v8 offset:4224
	ds_read_u16 v63, v8 offset:4480
	ds_read_u16 v64, v8 offset:4736
	ds_read_u16 v65, v8 offset:4992
	ds_read_u16 v66, v8 offset:5248
	ds_read_u16 v67, v8 offset:5504
	ds_read_u16 v68, v8 offset:5760
	ds_read_u16 v69, v8 offset:6016
	ds_read_u16 v70, v8 offset:6272
	ds_read_u16 v71, v8 offset:6528
	ds_read_u16 v72, v8 offset:6784
	ds_read_u16 v73, v8 offset:7040
	ds_read_u16 v74, v8 offset:7296
	ds_read_u16 v75, v8 offset:7552
	ds_read_u16 v76, v8 offset:7808
	ds_read_u16 v77, v8 offset:8064
	ds_read_u16 v78, v8 offset:8320
	ds_read_u16 v79, v8 offset:8576
	ds_read_u16 v80, v8 offset:8832
	ds_read_u16 v81, v8 offset:9088
	ds_read_u16 v82, v8 offset:9344
	ds_read_u16 v83, v8 offset:9600
	ds_read_u16 v84, v8 offset:9856
	ds_read_u16 v85, v8 offset:10112
	ds_read_u16 v86, v8 offset:10368
	ds_read_u16 v87, v8 offset:10624
	ds_read_u16 v88, v8 offset:10880
	ds_read_u16 v89, v8 offset:11136
	ds_read_u16 v90, v8 offset:11392
	ds_read_u16 v91, v8 offset:11648
	ds_read_u16 v92, v8 offset:11904
	s_mov_b32 s50, 0x3e800000
	s_waitcnt lgkmcnt(0)
	v_lshlrev_b32_e32 v58, 16, v58
	v_lshlrev_b32_e32 v59, 16, v59
	v_lshlrev_b32_e32 v60, 16, v60
	v_lshlrev_b32_e32 v61, 16, v61
	v_lshlrev_b32_e32 v62, 16, v62
	v_lshlrev_b32_e32 v63, 16, v63
	v_lshlrev_b32_e32 v64, 16, v64
	v_lshlrev_b32_e32 v65, 16, v65
	v_lshlrev_b32_e32 v66, 16, v66
	v_lshlrev_b32_e32 v67, 16, v67
	v_lshlrev_b32_e32 v68, 16, v68
	v_lshlrev_b32_e32 v69, 16, v69
	v_lshlrev_b32_e32 v70, 16, v70
	v_lshlrev_b32_e32 v71, 16, v71
	v_lshlrev_b32_e32 v72, 16, v72
	v_lshlrev_b32_e32 v73, 16, v73
	v_lshlrev_b32_e32 v74, 16, v74
	v_lshlrev_b32_e32 v75, 16, v75
	v_lshlrev_b32_e32 v76, 16, v76
	v_lshlrev_b32_e32 v77, 16, v77
	v_lshlrev_b32_e32 v78, 16, v78
	v_lshlrev_b32_e32 v79, 16, v79
	v_lshlrev_b32_e32 v80, 16, v80
	v_lshlrev_b32_e32 v81, 16, v81
	v_lshlrev_b32_e32 v82, 16, v82
	v_lshlrev_b32_e32 v83, 16, v83
	v_lshlrev_b32_e32 v84, 16, v84
	v_lshlrev_b32_e32 v85, 16, v85
	v_lshlrev_b32_e32 v86, 16, v86
	v_lshlrev_b32_e32 v87, 16, v87
	v_lshlrev_b32_e32 v88, 16, v88
	v_lshlrev_b32_e32 v89, 16, v89
	v_lshlrev_b32_e32 v90, 16, v90
	v_lshlrev_b32_e32 v91, 16, v91
	v_lshlrev_b32_e32 v92, 16, v92
	s_cmp_eq_u32 s42, 1
	s_cbranch_scc0 .Lpool_nz1
	v_mov_b32_e32 v60, 0
	v_mov_b32_e32 v59, 0
	v_mov_b32_e32 v58, 0
.Lpool_nz1:
	v_add_f32_e32 v93, v61, v60
	v_add_f32_e32 v93, v93, v59
	v_add_f32_e32 v93, v93, v58
	s_cmp_eq_u32 s42, 1
	s_cselect_b32 s51, 0x3f800000, s50
	v_fma_f32 v2, v93, s51, -v61
	v_add_f32_e32 v93, v93, v62
	v_sub_f32_e32 v93, v93, v58
	s_cmp_eq_u32 s42, 1
	s_cselect_b32 s51, 0x3f000000, s50
	v_fma_f32 v3, v93, s51, -v62
	v_cvt_pk_bf16_f32 v2, v2, v3
	ds_write_b16 v9, v2 offset:0
	ds_write_b16_d16_hi v9, v2 offset:144
	v_add_f32_e32 v93, v93, v63
	v_sub_f32_e32 v93, v93, v59
	s_cmp_eq_u32 s42, 1
	s_cselect_b32 s51, 0x3eaaaaab, s50
	v_fma_f32 v4, v93, s51, -v63
	v_add_f32_e32 v93, v93, v64
	v_sub_f32_e32 v93, v93, v60
	v_fma_f32 v5, v93, s50, -v64
	v_cvt_pk_bf16_f32 v4, v4, v5
	ds_write_b16 v9, v4 offset:288
	ds_write_b16_d16_hi v9, v4 offset:432
	v_add_f32_e32 v93, v93, v65
	v_sub_f32_e32 v93, v93, v61
	v_fma_f32 v2, v93, s50, -v65
	v_add_f32_e32 v93, v93, v66
	v_sub_f32_e32 v93, v93, v62
	v_fma_f32 v3, v93, s50, -v66
	v_cvt_pk_bf16_f32 v2, v2, v3
	ds_write_b16 v9, v2 offset:576
	ds_write_b16_d16_hi v9, v2 offset:720
	v_add_f32_e32 v93, v93, v67
	v_sub_f32_e32 v93, v93, v63
	v_fma_f32 v4, v93, s50, -v67
	v_add_f32_e32 v93, v93, v68
	v_sub_f32_e32 v93, v93, v64
	v_fma_f32 v5, v93, s50, -v68
	v_cvt_pk_bf16_f32 v4, v4, v5
	ds_write_b16 v9, v4 offset:864
	ds_write_b16_d16_hi v9, v4 offset:1008
	v_add_f32_e32 v93, v93, v69
	v_sub_f32_e32 v93, v93, v65
	v_fma_f32 v2, v93, s50, -v69
	v_add_f32_e32 v93, v93, v70
	v_sub_f32_e32 v93, v93, v66
	v_fma_f32 v3, v93, s50, -v70
	v_cvt_pk_bf16_f32 v2, v2, v3
	ds_write_b16 v9, v2 offset:1152
	ds_write_b16_d16_hi v9, v2 offset:1296
	v_add_f32_e32 v93, v93, v71
	v_sub_f32_e32 v93, v93, v67
	v_fma_f32 v4, v93, s50, -v71
	v_add_f32_e32 v93, v93, v72
	v_sub_f32_e32 v93, v93, v68
	v_fma_f32 v5, v93, s50, -v72
	v_cvt_pk_bf16_f32 v4, v4, v5
	ds_write_b16 v9, v4 offset:1440
	ds_write_b16_d16_hi v9, v4 offset:1584
	v_add_f32_e32 v93, v93, v73
	v_sub_f32_e32 v93, v93, v69
	v_fma_f32 v2, v93, s50, -v73
	v_add_f32_e32 v93, v93, v74
	v_sub_f32_e32 v93, v93, v70
	v_fma_f32 v3, v93, s50, -v74
	v_cvt_pk_bf16_f32 v2, v2, v3
	ds_write_b16 v9, v2 offset:1728
	ds_write_b16_d16_hi v9, v2 offset:1872
	v_add_f32_e32 v93, v93, v75
	v_sub_f32_e32 v93, v93, v71
	v_fma_f32 v4, v93, s50, -v75
	v_add_f32_e32 v93, v93, v76
	v_sub_f32_e32 v93, v93, v72
	v_fma_f32 v5, v93, s50, -v76
	v_cvt_pk_bf16_f32 v4, v4, v5
	ds_write_b16 v9, v4 offset:2016
	ds_write_b16_d16_hi v9, v4 offset:2160
	v_add_f32_e32 v93, v93, v77
	v_sub_f32_e32 v93, v93, v73
	v_fma_f32 v2, v93, s50, -v77
	v_add_f32_e32 v93, v93, v78
	v_sub_f32_e32 v93, v93, v74
	v_fma_f32 v3, v93, s50, -v78
	v_cvt_pk_bf16_f32 v2, v2, v3
	ds_write_b16 v9, v2 offset:2304
	ds_write_b16_d16_hi v9, v2 offset:2448
	v_add_f32_e32 v93, v93, v79
	v_sub_f32_e32 v93, v93, v75
	v_fma_f32 v4, v93, s50, -v79
	v_add_f32_e32 v93, v93, v80
	v_sub_f32_e32 v93, v93, v76
	v_fma_f32 v5, v93, s50, -v80
	v_cvt_pk_bf16_f32 v4, v4, v5
	ds_write_b16 v9, v4 offset:2592
	ds_write_b16_d16_hi v9, v4 offset:2736
	v_add_f32_e32 v93, v93, v81
	v_sub_f32_e32 v93, v93, v77
	v_fma_f32 v2, v93, s50, -v81
	v_add_f32_e32 v93, v93, v82
	v_sub_f32_e32 v93, v93, v78
	v_fma_f32 v3, v93, s50, -v82
	v_cvt_pk_bf16_f32 v2, v2, v3
	ds_write_b16 v9, v2 offset:2880
	ds_write_b16_d16_hi v9, v2 offset:3024
	v_add_f32_e32 v93, v93, v83
	v_sub_f32_e32 v93, v93, v79
	v_fma_f32 v4, v93, s50, -v83
	v_add_f32_e32 v93, v93, v84
	v_sub_f32_e32 v93, v93, v80
	v_fma_f32 v5, v93, s50, -v84
	v_cvt_pk_bf16_f32 v4, v4, v5
	ds_write_b16 v9, v4 offset:3168
	ds_write_b16_d16_hi v9, v4 offset:3312
	v_add_f32_e32 v93, v93, v85
	v_sub_f32_e32 v93, v93, v81
	v_fma_f32 v2, v93, s50, -v85
	v_add_f32_e32 v93, v93, v86
	v_sub_f32_e32 v93, v93, v82
	v_fma_f32 v3, v93, s50, -v86
	v_cvt_pk_bf16_f32 v2, v2, v3
	ds_write_b16 v9, v2 offset:3456
	ds_write_b16_d16_hi v9, v2 offset:3600
	v_add_f32_e32 v93, v93, v87
	v_sub_f32_e32 v93, v93, v83
	v_fma_f32 v4, v93, s50, -v87
	v_add_f32_e32 v93, v93, v88
	v_sub_f32_e32 v93, v93, v84
	v_fma_f32 v5, v93, s50, -v88
	v_cvt_pk_bf16_f32 v4, v4, v5
	ds_write_b16 v9, v4 offset:3744
	ds_write_b16_d16_hi v9, v4 offset:3888
	v_add_f32_e32 v93, v93, v89
	v_sub_f32_e32 v93, v93, v85
	v_fma_f32 v2, v93, s50, -v89
	v_add_f32_e32 v93, v93, v90
	v_sub_f32_e32 v93, v93, v86
	v_fma_f32 v3, v93, s50, -v90
	v_cvt_pk_bf16_f32 v2, v2, v3
	ds_write_b16 v9, v2 offset:4032
	ds_write_b16_d16_hi v9, v2 offset:4176
	v_add_f32_e32 v93, v93, v91
	v_sub_f32_e32 v93, v93, v87
	v_fma_f32 v4, v93, s50, -v91
	v_add_f32_e32 v93, v93, v92
	v_sub_f32_e32 v93, v93, v88
	v_fma_f32 v5, v93, s50, -v92
	v_cvt_pk_bf16_f32 v4, v4, v5
	ds_write_b16 v9, v4 offset:4320
	ds_write_b16_d16_hi v9, v4 offset:4464
	s_waitcnt lgkmcnt(0)
	ds_read_b128 v[78:81], v44 offset:0
	ds_read_b128 v[82:85], v44 offset:32
	ds_read_b128 v[86:89], v44 offset:64
	ds_read_b128 v[90:93], v44 offset:96
	v_lshl_add_u64 v[4:5], s[52:53], 0, v[10:11]
	s_waitcnt vmcnt(0)
	s_waitcnt lgkmcnt(0)
	v_mfma_f32_32x32x16_bf16 v[46:61], v[12:15], v[78:81], 0
	v_mfma_f32_32x32x16_bf16 v[62:77], v[16:19], v[78:81], 0
	global_load_dwordx2 v[12:13], v[4:5], off offset:128
	global_load_dwordx2 v[14:15], v[4:5], off offset:144
	global_load_dwordx2 v[16:17], v[4:5], off offset:160
	global_load_dwordx2 v[18:19], v[4:5], off offset:176
	v_mfma_f32_32x32x16_bf16 v[46:61], v[20:23], v[82:85], v[46:61]
	v_mfma_f32_32x32x16_bf16 v[62:77], v[24:27], v[82:85], v[62:77]
	global_load_dwordx2 v[20:21], v[4:5], off offset:192
	global_load_dwordx2 v[22:23], v[4:5], off offset:208
	global_load_dwordx2 v[24:25], v[4:5], off offset:224
	global_load_dwordx2 v[26:27], v[4:5], off offset:240
	v_mfma_f32_32x32x16_bf16 v[46:61], v[28:31], v[86:89], v[46:61]
	v_mfma_f32_32x32x16_bf16 v[62:77], v[32:35], v[86:89], v[62:77]
	v_mfma_f32_32x32x16_bf16 v[46:61], v[36:39], v[90:93], v[46:61]
	v_mfma_f32_32x32x16_bf16 v[62:77], v[40:43], v[90:93], v[62:77]
	s_nop 15
	s_waitcnt vmcnt(0)
	v_lshlrev_b32_e32 v32, 16, v12
	v_and_b32_e32 v33, 0xffff0000, v12
	v_lshlrev_b32_e32 v34, 16, v13
	v_and_b32_e32 v35, 0xffff0000, v13
	v_mul_f32_e32 v28, 0xbfb8aa3b, v32
	v_mul_f32_e32 v29, 0xbfb8aa3b, v33
	v_mul_f32_e32 v30, 0xbfb8aa3b, v34
	v_mul_f32_e32 v31, 0xbfb8aa3b, v35
	v_exp_f32_e32 v28, v28
	v_exp_f32_e32 v29, v29
	v_exp_f32_e32 v30, v30
	v_exp_f32_e32 v31, v31
	v_add_f32_e32 v28, 1.0, v28
	v_add_f32_e32 v29, 1.0, v29
	v_add_f32_e32 v30, 1.0, v30
	v_add_f32_e32 v31, 1.0, v31
	v_rcp_f32_e32 v28, v28
	v_rcp_f32_e32 v29, v29
	v_rcp_f32_e32 v30, v30
	v_rcp_f32_e32 v31, v31
	v_pk_mul_f32 v[28:29], v[32:33], v[28:29]
	v_pk_mul_f32 v[30:31], v[34:35], v[30:31]
	v_pk_mul_f32 v[28:29], v[46:47], v[28:29]
	v_pk_mul_f32 v[30:31], v[48:49], v[30:31]
	v_cvt_pk_bf16_f32 v36, v28, v29
	v_cvt_pk_bf16_f32 v37, v30, v31
	global_store_dwordx2 v[4:5], v[36:37], off offset:128
	v_lshlrev_b32_e32 v32, 16, v14
	v_and_b32_e32 v33, 0xffff0000, v14
	v_lshlrev_b32_e32 v34, 16, v15
	v_and_b32_e32 v35, 0xffff0000, v15
	v_mul_f32_e32 v28, 0xbfb8aa3b, v32
	v_mul_f32_e32 v29, 0xbfb8aa3b, v33
	v_mul_f32_e32 v30, 0xbfb8aa3b, v34
	v_mul_f32_e32 v31, 0xbfb8aa3b, v35
	v_exp_f32_e32 v28, v28
	v_exp_f32_e32 v29, v29
	v_exp_f32_e32 v30, v30
	v_exp_f32_e32 v31, v31
	v_add_f32_e32 v28, 1.0, v28
	v_add_f32_e32 v29, 1.0, v29
	v_add_f32_e32 v30, 1.0, v30
	v_add_f32_e32 v31, 1.0, v31
	v_rcp_f32_e32 v28, v28
	v_rcp_f32_e32 v29, v29
	v_rcp_f32_e32 v30, v30
	v_rcp_f32_e32 v31, v31
	v_pk_mul_f32 v[28:29], v[32:33], v[28:29]
	v_pk_mul_f32 v[30:31], v[34:35], v[30:31]
	v_pk_mul_f32 v[28:29], v[50:51], v[28:29]
	v_pk_mul_f32 v[30:31], v[52:53], v[30:31]
	v_cvt_pk_bf16_f32 v38, v28, v29
	v_cvt_pk_bf16_f32 v39, v30, v31
	global_store_dwordx2 v[4:5], v[38:39], off offset:144
	v_lshlrev_b32_e32 v32, 16, v16
	v_and_b32_e32 v33, 0xffff0000, v16
	v_lshlrev_b32_e32 v34, 16, v17
	v_and_b32_e32 v35, 0xffff0000, v17
	v_mul_f32_e32 v28, 0xbfb8aa3b, v32
	v_mul_f32_e32 v29, 0xbfb8aa3b, v33
	v_mul_f32_e32 v30, 0xbfb8aa3b, v34
	v_mul_f32_e32 v31, 0xbfb8aa3b, v35
	v_exp_f32_e32 v28, v28
	v_exp_f32_e32 v29, v29
	v_exp_f32_e32 v30, v30
	v_exp_f32_e32 v31, v31
	v_add_f32_e32 v28, 1.0, v28
	v_add_f32_e32 v29, 1.0, v29
	v_add_f32_e32 v30, 1.0, v30
	v_add_f32_e32 v31, 1.0, v31
	v_rcp_f32_e32 v28, v28
	v_rcp_f32_e32 v29, v29
	v_rcp_f32_e32 v30, v30
	v_rcp_f32_e32 v31, v31
	v_pk_mul_f32 v[28:29], v[32:33], v[28:29]
	v_pk_mul_f32 v[30:31], v[34:35], v[30:31]
	v_pk_mul_f32 v[28:29], v[54:55], v[28:29]
	v_pk_mul_f32 v[30:31], v[56:57], v[30:31]
	v_cvt_pk_bf16_f32 v36, v28, v29
	v_cvt_pk_bf16_f32 v37, v30, v31
	global_store_dwordx2 v[4:5], v[36:37], off offset:160
	v_lshlrev_b32_e32 v32, 16, v18
	v_and_b32_e32 v33, 0xffff0000, v18
	v_lshlrev_b32_e32 v34, 16, v19
	v_and_b32_e32 v35, 0xffff0000, v19
	v_mul_f32_e32 v28, 0xbfb8aa3b, v32
	v_mul_f32_e32 v29, 0xbfb8aa3b, v33
	v_mul_f32_e32 v30, 0xbfb8aa3b, v34
	v_mul_f32_e32 v31, 0xbfb8aa3b, v35
	v_exp_f32_e32 v28, v28
	v_exp_f32_e32 v29, v29
	v_exp_f32_e32 v30, v30
	v_exp_f32_e32 v31, v31
	v_add_f32_e32 v28, 1.0, v28
	v_add_f32_e32 v29, 1.0, v29
	v_add_f32_e32 v30, 1.0, v30
	v_add_f32_e32 v31, 1.0, v31
	v_rcp_f32_e32 v28, v28
	v_rcp_f32_e32 v29, v29
	v_rcp_f32_e32 v30, v30
	v_rcp_f32_e32 v31, v31
	v_pk_mul_f32 v[28:29], v[32:33], v[28:29]
	v_pk_mul_f32 v[30:31], v[34:35], v[30:31]
	v_pk_mul_f32 v[28:29], v[58:59], v[28:29]
	v_pk_mul_f32 v[30:31], v[60:61], v[30:31]
	v_cvt_pk_bf16_f32 v38, v28, v29
	v_cvt_pk_bf16_f32 v39, v30, v31
	global_store_dwordx2 v[4:5], v[38:39], off offset:176
	v_lshlrev_b32_e32 v32, 16, v20
	v_and_b32_e32 v33, 0xffff0000, v20
	v_lshlrev_b32_e32 v34, 16, v21
	v_and_b32_e32 v35, 0xffff0000, v21
	v_mul_f32_e32 v28, 0xbfb8aa3b, v32
	v_mul_f32_e32 v29, 0xbfb8aa3b, v33
	v_mul_f32_e32 v30, 0xbfb8aa3b, v34
	v_mul_f32_e32 v31, 0xbfb8aa3b, v35
	v_exp_f32_e32 v28, v28
	v_exp_f32_e32 v29, v29
	v_exp_f32_e32 v30, v30
	v_exp_f32_e32 v31, v31
	v_add_f32_e32 v28, 1.0, v28
	v_add_f32_e32 v29, 1.0, v29
	v_add_f32_e32 v30, 1.0, v30
	v_add_f32_e32 v31, 1.0, v31
	v_rcp_f32_e32 v28, v28
	v_rcp_f32_e32 v29, v29
	v_rcp_f32_e32 v30, v30
	v_rcp_f32_e32 v31, v31
	v_pk_mul_f32 v[28:29], v[32:33], v[28:29]
	v_pk_mul_f32 v[30:31], v[34:35], v[30:31]
	v_pk_mul_f32 v[28:29], v[62:63], v[28:29]
	v_pk_mul_f32 v[30:31], v[64:65], v[30:31]
	v_cvt_pk_bf16_f32 v36, v28, v29
	v_cvt_pk_bf16_f32 v37, v30, v31
	global_store_dwordx2 v[4:5], v[36:37], off offset:192
	v_lshlrev_b32_e32 v32, 16, v22
	v_and_b32_e32 v33, 0xffff0000, v22
	v_lshlrev_b32_e32 v34, 16, v23
	v_and_b32_e32 v35, 0xffff0000, v23
	v_mul_f32_e32 v28, 0xbfb8aa3b, v32
	v_mul_f32_e32 v29, 0xbfb8aa3b, v33
	v_mul_f32_e32 v30, 0xbfb8aa3b, v34
	v_mul_f32_e32 v31, 0xbfb8aa3b, v35
	v_exp_f32_e32 v28, v28
	v_exp_f32_e32 v29, v29
	v_exp_f32_e32 v30, v30
	v_exp_f32_e32 v31, v31
	v_add_f32_e32 v28, 1.0, v28
	v_add_f32_e32 v29, 1.0, v29
	v_add_f32_e32 v30, 1.0, v30
	v_add_f32_e32 v31, 1.0, v31
	v_rcp_f32_e32 v28, v28
	v_rcp_f32_e32 v29, v29
	v_rcp_f32_e32 v30, v30
	v_rcp_f32_e32 v31, v31
	v_pk_mul_f32 v[28:29], v[32:33], v[28:29]
	v_pk_mul_f32 v[30:31], v[34:35], v[30:31]
	v_pk_mul_f32 v[28:29], v[66:67], v[28:29]
	v_pk_mul_f32 v[30:31], v[68:69], v[30:31]
	v_cvt_pk_bf16_f32 v38, v28, v29
	v_cvt_pk_bf16_f32 v39, v30, v31
	global_store_dwordx2 v[4:5], v[38:39], off offset:208
	v_lshlrev_b32_e32 v32, 16, v24
	v_and_b32_e32 v33, 0xffff0000, v24
	v_lshlrev_b32_e32 v34, 16, v25
	v_and_b32_e32 v35, 0xffff0000, v25
	v_mul_f32_e32 v28, 0xbfb8aa3b, v32
	v_mul_f32_e32 v29, 0xbfb8aa3b, v33
	v_mul_f32_e32 v30, 0xbfb8aa3b, v34
	v_mul_f32_e32 v31, 0xbfb8aa3b, v35
	v_exp_f32_e32 v28, v28
	v_exp_f32_e32 v29, v29
	v_exp_f32_e32 v30, v30
	v_exp_f32_e32 v31, v31
	v_add_f32_e32 v28, 1.0, v28
	v_add_f32_e32 v29, 1.0, v29
	v_add_f32_e32 v30, 1.0, v30
	v_add_f32_e32 v31, 1.0, v31
	v_rcp_f32_e32 v28, v28
	v_rcp_f32_e32 v29, v29
	v_rcp_f32_e32 v30, v30
	v_rcp_f32_e32 v31, v31
	v_pk_mul_f32 v[28:29], v[32:33], v[28:29]
	v_pk_mul_f32 v[30:31], v[34:35], v[30:31]
	v_pk_mul_f32 v[28:29], v[70:71], v[28:29]
	v_pk_mul_f32 v[30:31], v[72:73], v[30:31]
	v_cvt_pk_bf16_f32 v36, v28, v29
	v_cvt_pk_bf16_f32 v37, v30, v31
	global_store_dwordx2 v[4:5], v[36:37], off offset:224
	v_lshlrev_b32_e32 v32, 16, v26
	v_and_b32_e32 v33, 0xffff0000, v26
	v_lshlrev_b32_e32 v34, 16, v27
	v_and_b32_e32 v35, 0xffff0000, v27
	v_mul_f32_e32 v28, 0xbfb8aa3b, v32
	v_mul_f32_e32 v29, 0xbfb8aa3b, v33
	v_mul_f32_e32 v30, 0xbfb8aa3b, v34
	v_mul_f32_e32 v31, 0xbfb8aa3b, v35
	v_exp_f32_e32 v28, v28
	v_exp_f32_e32 v29, v29
	v_exp_f32_e32 v30, v30
	v_exp_f32_e32 v31, v31
	v_add_f32_e32 v28, 1.0, v28
	v_add_f32_e32 v29, 1.0, v29
	v_add_f32_e32 v30, 1.0, v30
	v_add_f32_e32 v31, 1.0, v31
	v_rcp_f32_e32 v28, v28
	v_rcp_f32_e32 v29, v29
	v_rcp_f32_e32 v30, v30
	v_rcp_f32_e32 v31, v31
	v_pk_mul_f32 v[28:29], v[32:33], v[28:29]
	v_pk_mul_f32 v[30:31], v[34:35], v[30:31]
	v_pk_mul_f32 v[28:29], v[74:75], v[28:29]
	v_pk_mul_f32 v[30:31], v[76:77], v[30:31]
	v_cvt_pk_bf16_f32 v38, v28, v29
	v_cvt_pk_bf16_f32 v39, v30, v31
	global_store_dwordx2 v[4:5], v[38:39], off offset:240
	s_barrier
	s_add_u32 s46, s44, 0x100
	s_addc_u32 s47, s45, 0
	s_add_i32 s43, s48, 0x0
	v_lshl_add_u64 v[4:5], s[46:47], 0, v[6:7]
	s_mov_b32 m0, s43
	s_nop 0
	global_load_lds_dwordx4 v[4:5], off
	s_add_u32 s46, s44, 0x4100
	s_addc_u32 s47, s45, 0
	s_add_i32 s43, s48, 0x2000
	v_lshl_add_u64 v[4:5], s[46:47], 0, v[6:7]
	s_mov_b32 m0, s43
	s_nop 0
	global_load_lds_dwordx4 v[4:5], off
	s_add_u32 s46, s44, 0x8100
	s_addc_u32 s47, s45, 0
	s_add_i32 s43, s48, 0x4000
	v_lshl_add_u64 v[4:5], s[46:47], 0, v[6:7]
	s_mov_b32 m0, s43
	s_nop 0
	global_load_lds_dwordx4 v[4:5], off
	s_add_u32 s46, s44, 0xc100
	s_addc_u32 s47, s45, 0
	s_add_i32 s43, s48, 0x6000
	v_lshl_add_u64 v[4:5], s[46:47], 0, v[6:7]
	s_mov_b32 m0, s43
	s_nop 0
	global_load_lds_dwordx4 v[4:5], off
	s_add_u32 s46, s44, 0x10100
	s_addc_u32 s47, s45, 0
	s_add_i32 s43, s48, 0x8000
	v_lshl_add_u64 v[4:5], s[46:47], 0, v[6:7]
	s_mov_b32 m0, s43
	s_nop 0
	global_load_lds_dwordx4 v[4:5], off
	s_add_u32 s46, s44, 0x14100
	s_addc_u32 s47, s45, 0
	s_add_i32 s43, s48, 0xa000
	v_lshl_add_u64 v[4:5], s[46:47], 0, v[6:7]
	s_mov_b32 m0, s43
	s_nop 0
	global_load_lds_dwordx4 v[4:5], off
	s_add_u32 s46, s44, 0x18100
	s_addc_u32 s47, s45, 0
	s_add_i32 s43, s48, 0xc000
	v_lshl_add_u64 v[4:5], s[46:47], 0, v[6:7]
	s_mov_b32 m0, s43
	s_nop 0
	global_load_lds_dwordx4 v[4:5], off
	s_add_u32 s46, s44, 0x1c100
	s_addc_u32 s47, s45, 0
	s_add_i32 s43, s48, 0xe000
	v_lshl_add_u64 v[4:5], s[46:47], 0, v[6:7]
	s_mov_b32 m0, s43
	s_nop 0
	global_load_lds_dwordx4 v[4:5], off
	s_cmp_lt_u32 s41, 4
	s_cbranch_scc0 .Lpool_dma_done1
	s_add_u32 s46, s44, 0x20100
	s_addc_u32 s47, s45, 0
	s_add_i32 s43, s48, 0x10000
	v_lshl_add_u64 v[4:5], s[46:47], 0, v[6:7]
	s_mov_b32 m0, s43
	s_nop 0
	global_load_lds_dwordx4 v[4:5], off
.Lpool_dma_done1:
	s_waitcnt vmcnt(0)
	s_barrier
	v_readlane_b32 s54, v250, 27
	v_readlane_b32 s55, v250, 28
	v_mov_b32_e32 v2, v45
	v_mov_b32_e32 v3, 0
	s_nop 1
	v_lshl_add_u64 v[4:5], s[54:55], 0, v[2:3]
	global_load_dwordx4 v[12:15], v[4:5], off offset:-2048
	global_load_dwordx4 v[16:19], v[4:5], off offset:2048
	global_load_dwordx4 v[20:23], v[4:5], off offset:-2016
	global_load_dwordx4 v[24:27], v[4:5], off offset:2080
	global_load_dwordx4 v[28:31], v[4:5], off offset:-1984
	global_load_dwordx4 v[32:35], v[4:5], off offset:2112
	global_load_dwordx4 v[36:39], v[4:5], off offset:-1952
	global_load_dwordx4 v[40:43], v[4:5], off offset:2144
	ds_read_u16 v54, v8 offset:2048
	ds_read_u16 v55, v8 offset:2304
	ds_read_u16 v56, v8 offset:2560
	ds_read_u16 v57, v8 offset:2816
	ds_read_u16 v58, v8 offset:3072
	ds_read_u16 v59, v8 offset:3328
	ds_read_u16 v60, v8 offset:3584
	ds_read_u16 v61, v8 offset:3840
	ds_read_u16 v62, v8 offset:4096
	ds_read_u16 v63, v8 offset:4352
	ds_read_u16 v64, v8 offset:4608
	ds_read_u16 v65, v8 offset:4864
	ds_read_u16 v66, v8 offset:5120
	ds_read_u16 v67, v8 offset:5376
	ds_read_u16 v68, v8 offset:5632
	ds_read_u16 v69, v8 offset:5888
	ds_read_u16 v70, v8 offset:6144
	ds_read_u16 v71, v8 offset:6400
	ds_read_u16 v72, v8 offset:6656
	ds_read_u16 v73, v8 offset:6912
	ds_read_u16 v74, v8 offset:7168
	ds_read_u16 v75, v8 offset:7424
	ds_read_u16 v76, v8 offset:7680
	ds_read_u16 v77, v8 offset:7936
	ds_read_u16 v78, v8 offset:8192
	ds_read_u16 v79, v8 offset:8448
	ds_read_u16 v80, v8 offset:8704
	ds_read_u16 v81, v8 offset:8960
	ds_read_u16 v82, v8 offset:9216
	ds_read_u16 v83, v8 offset:9472
	ds_read_u16 v84, v8 offset:9728
	ds_read_u16 v85, v8 offset:9984
	ds_read_u16 v86, v8 offset:10240
	ds_read_u16 v87, v8 offset:10496
	ds_read_u16 v88, v8 offset:10752
	ds_read_u16 v89, v8 offset:11008
	ds_read_u16 v90, v8 offset:11264
	ds_read_u16 v91, v8 offset:11520
	ds_read_u16 v92, v8 offset:11776
	s_mov_b32 s50, 0x3e000000
	s_waitcnt lgkmcnt(0)
	v_lshlrev_b32_e32 v54, 16, v54
	v_lshlrev_b32_e32 v55, 16, v55
	v_lshlrev_b32_e32 v56, 16, v56
	v_lshlrev_b32_e32 v57, 16, v57
	v_lshlrev_b32_e32 v58, 16, v58
	v_lshlrev_b32_e32 v59, 16, v59
	v_lshlrev_b32_e32 v60, 16, v60
	v_lshlrev_b32_e32 v61, 16, v61
	v_lshlrev_b32_e32 v62, 16, v62
	v_lshlrev_b32_e32 v63, 16, v63
	v_lshlrev_b32_e32 v64, 16, v64
	v_lshlrev_b32_e32 v65, 16, v65
	v_lshlrev_b32_e32 v66, 16, v66
	v_lshlrev_b32_e32 v67, 16, v67
	v_lshlrev_b32_e32 v68, 16, v68
	v_lshlrev_b32_e32 v69, 16, v69
	v_lshlrev_b32_e32 v70, 16, v70
	v_lshlrev_b32_e32 v71, 16, v71
	v_lshlrev_b32_e32 v72, 16, v72
	v_lshlrev_b32_e32 v73, 16, v73
	v_lshlrev_b32_e32 v74, 16, v74
	v_lshlrev_b32_e32 v75, 16, v75
	v_lshlrev_b32_e32 v76, 16, v76
	v_lshlrev_b32_e32 v77, 16, v77
	v_lshlrev_b32_e32 v78, 16, v78
	v_lshlrev_b32_e32 v79, 16, v79
	v_lshlrev_b32_e32 v80, 16, v80
	v_lshlrev_b32_e32 v81, 16, v81
	v_lshlrev_b32_e32 v82, 16, v82
	v_lshlrev_b32_e32 v83, 16, v83
	v_lshlrev_b32_e32 v84, 16, v84
	v_lshlrev_b32_e32 v85, 16, v85
	v_lshlrev_b32_e32 v86, 16, v86
	v_lshlrev_b32_e32 v87, 16, v87
	v_lshlrev_b32_e32 v88, 16, v88
	v_lshlrev_b32_e32 v89, 16, v89
	v_lshlrev_b32_e32 v90, 16, v90
	v_lshlrev_b32_e32 v91, 16, v91
	v_lshlrev_b32_e32 v92, 16, v92
	s_cmp_eq_u32 s42, 1
	s_cbranch_scc0 .Lpool_nz2
	v_mov_b32_e32 v60, 0
	v_mov_b32_e32 v59, 0
	v_mov_b32_e32 v58, 0
	v_mov_b32_e32 v57, 0
	v_mov_b32_e32 v56, 0
	v_mov_b32_e32 v55, 0
	v_mov_b32_e32 v54, 0
.Lpool_nz2:
	v_add_f32_e32 v93, v61, v60
	v_add_f32_e32 v93, v93, v59
	v_add_f32_e32 v93, v93, v58
	v_add_f32_e32 v93, v93, v57
	v_add_f32_e32 v93, v93, v56
	v_add_f32_e32 v93, v93, v55
	v_add_f32_e32 v93, v93, v54
	s_cmp_eq_u32 s42, 1
	s_cselect_b32 s51, 0x3f800000, s50
	v_fma_f32 v2, v93, s51, -v61
	v_add_f32_e32 v93, v93, v62
	v_sub_f32_e32 v93, v93, v54
	s_cmp_eq_u32 s42, 1
	s_cselect_b32 s51, 0x3f000000, s50
	v_fma_f32 v3, v93, s51, -v62
	v_cvt_pk_bf16_f32 v2, v2, v3
	ds_write_b16 v9, v2 offset:0
	ds_write_b16_d16_hi v9, v2 offset:144
	v_add_f32_e32 v93, v93, v63
	v_sub_f32_e32 v93, v93, v55
	s_cmp_eq_u32 s42, 1
	s_cselect_b32 s51, 0x3eaaaaab, s50
	v_fma_f32 v4, v93, s51, -v63
	v_add_f32_e32 v93, v93, v64
	v_sub_f32_e32 v93, v93, v56
	s_cmp_eq_u32 s42, 1
	s_cselect_b32 s51, 0x3e800000, s50
	v_fma_f32 v5, v93, s51, -v64
	v_cvt_pk_bf16_f32 v4, v4, v5
	ds_write_b16 v9, v4 offset:288
	ds_write_b16_d16_hi v9, v4 offset:432
	v_add_f32_e32 v93, v93, v65
	v_sub_f32_e32 v93, v93, v57
	s_cmp_eq_u32 s42, 1
	s_cselect_b32 s51, 0x3e4ccccd, s50
	v_fma_f32 v2, v93, s51, -v65
	v_add_f32_e32 v93, v93, v66
	v_sub_f32_e32 v93, v93, v58
	s_cmp_eq_u32 s42, 1
	s_cselect_b32 s51, 0x3e2aaaab, s50
	v_fma_f32 v3, v93, s51, -v66
	v_cvt_pk_bf16_f32 v2, v2, v3
	ds_write_b16 v9, v2 offset:576
	ds_write_b16_d16_hi v9, v2 offset:720
	v_add_f32_e32 v93, v93, v67
	v_sub_f32_e32 v93, v93, v59
	s_cmp_eq_u32 s42, 1
	s_cselect_b32 s51, 0x3e124925, s50
	v_fma_f32 v4, v93, s51, -v67
	v_add_f32_e32 v93, v93, v68
	v_sub_f32_e32 v93, v93, v60
	v_fma_f32 v5, v93, s50, -v68
	v_cvt_pk_bf16_f32 v4, v4, v5
	ds_write_b16 v9, v4 offset:864
	ds_write_b16_d16_hi v9, v4 offset:1008
	v_add_f32_e32 v93, v93, v69
	v_sub_f32_e32 v93, v93, v61
	v_fma_f32 v2, v93, s50, -v69
	v_add_f32_e32 v93, v93, v70
	v_sub_f32_e32 v93, v93, v62
	v_fma_f32 v3, v93, s50, -v70
	v_cvt_pk_bf16_f32 v2, v2, v3
	ds_write_b16 v9, v2 offset:1152
	ds_write_b16_d16_hi v9, v2 offset:1296
	v_add_f32_e32 v93, v93, v71
	v_sub_f32_e32 v93, v93, v63
	v_fma_f32 v4, v93, s50, -v71
	v_add_f32_e32 v93, v93, v72
	v_sub_f32_e32 v93, v93, v64
	v_fma_f32 v5, v93, s50, -v72
	v_cvt_pk_bf16_f32 v4, v4, v5
	ds_write_b16 v9, v4 offset:1440
	ds_write_b16_d16_hi v9, v4 offset:1584
	v_add_f32_e32 v93, v93, v73
	v_sub_f32_e32 v93, v93, v65
	v_fma_f32 v2, v93, s50, -v73
	v_add_f32_e32 v93, v93, v74
	v_sub_f32_e32 v93, v93, v66
	v_fma_f32 v3, v93, s50, -v74
	v_cvt_pk_bf16_f32 v2, v2, v3
	ds_write_b16 v9, v2 offset:1728
	ds_write_b16_d16_hi v9, v2 offset:1872
	v_add_f32_e32 v93, v93, v75
	v_sub_f32_e32 v93, v93, v67
	v_fma_f32 v4, v93, s50, -v75
	v_add_f32_e32 v93, v93, v76
	v_sub_f32_e32 v93, v93, v68
	v_fma_f32 v5, v93, s50, -v76
	v_cvt_pk_bf16_f32 v4, v4, v5
	ds_write_b16 v9, v4 offset:2016
	ds_write_b16_d16_hi v9, v4 offset:2160
	v_add_f32_e32 v93, v93, v77
	v_sub_f32_e32 v93, v93, v69
	v_fma_f32 v2, v93, s50, -v77
	v_add_f32_e32 v93, v93, v78
	v_sub_f32_e32 v93, v93, v70
	v_fma_f32 v3, v93, s50, -v78
	v_cvt_pk_bf16_f32 v2, v2, v3
	ds_write_b16 v9, v2 offset:2304
	ds_write_b16_d16_hi v9, v2 offset:2448
	v_add_f32_e32 v93, v93, v79
	v_sub_f32_e32 v93, v93, v71
	v_fma_f32 v4, v93, s50, -v79
	v_add_f32_e32 v93, v93, v80
	v_sub_f32_e32 v93, v93, v72
	v_fma_f32 v5, v93, s50, -v80
	v_cvt_pk_bf16_f32 v4, v4, v5
	ds_write_b16 v9, v4 offset:2592
	ds_write_b16_d16_hi v9, v4 offset:2736
	v_add_f32_e32 v93, v93, v81
	v_sub_f32_e32 v93, v93, v73
	v_fma_f32 v2, v93, s50, -v81
	v_add_f32_e32 v93, v93, v82
	v_sub_f32_e32 v93, v93, v74
	v_fma_f32 v3, v93, s50, -v82
	v_cvt_pk_bf16_f32 v2, v2, v3
	ds_write_b16 v9, v2 offset:2880
	ds_write_b16_d16_hi v9, v2 offset:3024
	v_add_f32_e32 v93, v93, v83
	v_sub_f32_e32 v93, v93, v75
	v_fma_f32 v4, v93, s50, -v83
	v_add_f32_e32 v93, v93, v84
	v_sub_f32_e32 v93, v93, v76
	v_fma_f32 v5, v93, s50, -v84
	v_cvt_pk_bf16_f32 v4, v4, v5
	ds_write_b16 v9, v4 offset:3168
	ds_write_b16_d16_hi v9, v4 offset:3312
	v_add_f32_e32 v93, v93, v85
	v_sub_f32_e32 v93, v93, v77
	v_fma_f32 v2, v93, s50, -v85
	v_add_f32_e32 v93, v93, v86
	v_sub_f32_e32 v93, v93, v78
	v_fma_f32 v3, v93, s50, -v86
	v_cvt_pk_bf16_f32 v2, v2, v3
	ds_write_b16 v9, v2 offset:3456
	ds_write_b16_d16_hi v9, v2 offset:3600
	v_add_f32_e32 v93, v93, v87
	v_sub_f32_e32 v93, v93, v79
	v_fma_f32 v4, v93, s50, -v87
	v_add_f32_e32 v93, v93, v88
	v_sub_f32_e32 v93, v93, v80
	v_fma_f32 v5, v93, s50, -v88
	v_cvt_pk_bf16_f32 v4, v4, v5
	ds_write_b16 v9, v4 offset:3744
	ds_write_b16_d16_hi v9, v4 offset:3888
	v_add_f32_e32 v93, v93, v89
	v_sub_f32_e32 v93, v93, v81
	v_fma_f32 v2, v93, s50, -v89
	v_add_f32_e32 v93, v93, v90
	v_sub_f32_e32 v93, v93, v82
	v_fma_f32 v3, v93, s50, -v90
	v_cvt_pk_bf16_f32 v2, v2, v3
	ds_write_b16 v9, v2 offset:4032
	ds_write_b16_d16_hi v9, v2 offset:4176
	v_add_f32_e32 v93, v93, v91
	v_sub_f32_e32 v93, v93, v83
	v_fma_f32 v4, v93, s50, -v91
	v_add_f32_e32 v93, v93, v92
	v_sub_f32_e32 v93, v93, v84
	v_fma_f32 v5, v93, s50, -v92
	v_cvt_pk_bf16_f32 v4, v4, v5
	ds_write_b16 v9, v4 offset:4320
	ds_write_b16_d16_hi v9, v4 offset:4464
	s_waitcnt lgkmcnt(0)
	ds_read_b128 v[78:81], v44 offset:0
	ds_read_b128 v[82:85], v44 offset:32
	ds_read_b128 v[86:89], v44 offset:64
	ds_read_b128 v[90:93], v44 offset:96
	v_lshl_add_u64 v[4:5], s[52:53], 0, v[10:11]
	s_waitcnt vmcnt(0)
	s_waitcnt lgkmcnt(0)
	v_mfma_f32_32x32x16_bf16 v[46:61], v[12:15], v[78:81], 0
	v_mfma_f32_32x32x16_bf16 v[62:77], v[16:19], v[78:81], 0
	global_load_dwordx2 v[12:13], v[4:5], off offset:256
	global_load_dwordx2 v[14:15], v[4:5], off offset:272
	global_load_dwordx2 v[16:17], v[4:5], off offset:288
	global_load_dwordx2 v[18:19], v[4:5], off offset:304
	v_mfma_f32_32x32x16_bf16 v[46:61], v[20:23], v[82:85], v[46:61]
	v_mfma_f32_32x32x16_bf16 v[62:77], v[24:27], v[82:85], v[62:77]
	global_load_dwordx2 v[20:21], v[4:5], off offset:320
	global_load_dwordx2 v[22:23], v[4:5], off offset:336
	global_load_dwordx2 v[24:25], v[4:5], off offset:352
	global_load_dwordx2 v[26:27], v[4:5], off offset:368
	v_mfma_f32_32x32x16_bf16 v[46:61], v[28:31], v[86:89], v[46:61]
	v_mfma_f32_32x32x16_bf16 v[62:77], v[32:35], v[86:89], v[62:77]
	v_mfma_f32_32x32x16_bf16 v[46:61], v[36:39], v[90:93], v[46:61]
	v_mfma_f32_32x32x16_bf16 v[62:77], v[40:43], v[90:93], v[62:77]
	s_nop 15
	s_waitcnt vmcnt(0)
	v_lshlrev_b32_e32 v32, 16, v12
	v_and_b32_e32 v33, 0xffff0000, v12
	v_lshlrev_b32_e32 v34, 16, v13
	v_and_b32_e32 v35, 0xffff0000, v13
	v_mul_f32_e32 v28, 0xbfb8aa3b, v32
	v_mul_f32_e32 v29, 0xbfb8aa3b, v33
	v_mul_f32_e32 v30, 0xbfb8aa3b, v34
	v_mul_f32_e32 v31, 0xbfb8aa3b, v35
	v_exp_f32_e32 v28, v28
	v_exp_f32_e32 v29, v29
	v_exp_f32_e32 v30, v30
	v_exp_f32_e32 v31, v31
	v_add_f32_e32 v28, 1.0, v28
	v_add_f32_e32 v29, 1.0, v29
	v_add_f32_e32 v30, 1.0, v30
	v_add_f32_e32 v31, 1.0, v31
	v_rcp_f32_e32 v28, v28
	v_rcp_f32_e32 v29, v29
	v_rcp_f32_e32 v30, v30
	v_rcp_f32_e32 v31, v31
	v_pk_mul_f32 v[28:29], v[32:33], v[28:29]
	v_pk_mul_f32 v[30:31], v[34:35], v[30:31]
	v_pk_mul_f32 v[28:29], v[46:47], v[28:29]
	v_pk_mul_f32 v[30:31], v[48:49], v[30:31]
	v_cvt_pk_bf16_f32 v36, v28, v29
	v_cvt_pk_bf16_f32 v37, v30, v31
	global_store_dwordx2 v[4:5], v[36:37], off offset:256
	v_lshlrev_b32_e32 v32, 16, v14
	v_and_b32_e32 v33, 0xffff0000, v14
	v_lshlrev_b32_e32 v34, 16, v15
	v_and_b32_e32 v35, 0xffff0000, v15
	v_mul_f32_e32 v28, 0xbfb8aa3b, v32
	v_mul_f32_e32 v29, 0xbfb8aa3b, v33
	v_mul_f32_e32 v30, 0xbfb8aa3b, v34
	v_mul_f32_e32 v31, 0xbfb8aa3b, v35
	v_exp_f32_e32 v28, v28
	v_exp_f32_e32 v29, v29
	v_exp_f32_e32 v30, v30
	v_exp_f32_e32 v31, v31
	v_add_f32_e32 v28, 1.0, v28
	v_add_f32_e32 v29, 1.0, v29
	v_add_f32_e32 v30, 1.0, v30
	v_add_f32_e32 v31, 1.0, v31
	v_rcp_f32_e32 v28, v28
	v_rcp_f32_e32 v29, v29
	v_rcp_f32_e32 v30, v30
	v_rcp_f32_e32 v31, v31
	v_pk_mul_f32 v[28:29], v[32:33], v[28:29]
	v_pk_mul_f32 v[30:31], v[34:35], v[30:31]
	v_pk_mul_f32 v[28:29], v[50:51], v[28:29]
	v_pk_mul_f32 v[30:31], v[52:53], v[30:31]
	v_cvt_pk_bf16_f32 v38, v28, v29
	v_cvt_pk_bf16_f32 v39, v30, v31
	global_store_dwordx2 v[4:5], v[38:39], off offset:272
	v_lshlrev_b32_e32 v32, 16, v16
	v_and_b32_e32 v33, 0xffff0000, v16
	v_lshlrev_b32_e32 v34, 16, v17
	v_and_b32_e32 v35, 0xffff0000, v17
	v_mul_f32_e32 v28, 0xbfb8aa3b, v32
	v_mul_f32_e32 v29, 0xbfb8aa3b, v33
	v_mul_f32_e32 v30, 0xbfb8aa3b, v34
	v_mul_f32_e32 v31, 0xbfb8aa3b, v35
	v_exp_f32_e32 v28, v28
	v_exp_f32_e32 v29, v29
	v_exp_f32_e32 v30, v30
	v_exp_f32_e32 v31, v31
	v_add_f32_e32 v28, 1.0, v28
	v_add_f32_e32 v29, 1.0, v29
	v_add_f32_e32 v30, 1.0, v30
	v_add_f32_e32 v31, 1.0, v31
	v_rcp_f32_e32 v28, v28
	v_rcp_f32_e32 v29, v29
	v_rcp_f32_e32 v30, v30
	v_rcp_f32_e32 v31, v31
	v_pk_mul_f32 v[28:29], v[32:33], v[28:29]
	v_pk_mul_f32 v[30:31], v[34:35], v[30:31]
	v_pk_mul_f32 v[28:29], v[54:55], v[28:29]
	v_pk_mul_f32 v[30:31], v[56:57], v[30:31]
	v_cvt_pk_bf16_f32 v36, v28, v29
	v_cvt_pk_bf16_f32 v37, v30, v31
	global_store_dwordx2 v[4:5], v[36:37], off offset:288
	v_lshlrev_b32_e32 v32, 16, v18
	v_and_b32_e32 v33, 0xffff0000, v18
	v_lshlrev_b32_e32 v34, 16, v19
	v_and_b32_e32 v35, 0xffff0000, v19
	v_mul_f32_e32 v28, 0xbfb8aa3b, v32
	v_mul_f32_e32 v29, 0xbfb8aa3b, v33
	v_mul_f32_e32 v30, 0xbfb8aa3b, v34
	v_mul_f32_e32 v31, 0xbfb8aa3b, v35
	v_exp_f32_e32 v28, v28
	v_exp_f32_e32 v29, v29
	v_exp_f32_e32 v30, v30
	v_exp_f32_e32 v31, v31
	v_add_f32_e32 v28, 1.0, v28
	v_add_f32_e32 v29, 1.0, v29
	v_add_f32_e32 v30, 1.0, v30
	v_add_f32_e32 v31, 1.0, v31
	v_rcp_f32_e32 v28, v28
	v_rcp_f32_e32 v29, v29
	v_rcp_f32_e32 v30, v30
	v_rcp_f32_e32 v31, v31
	v_pk_mul_f32 v[28:29], v[32:33], v[28:29]
	v_pk_mul_f32 v[30:31], v[34:35], v[30:31]
	v_pk_mul_f32 v[28:29], v[58:59], v[28:29]
	v_pk_mul_f32 v[30:31], v[60:61], v[30:31]
	v_cvt_pk_bf16_f32 v38, v28, v29
	v_cvt_pk_bf16_f32 v39, v30, v31
	global_store_dwordx2 v[4:5], v[38:39], off offset:304
	v_lshlrev_b32_e32 v32, 16, v20
	v_and_b32_e32 v33, 0xffff0000, v20
	v_lshlrev_b32_e32 v34, 16, v21
	v_and_b32_e32 v35, 0xffff0000, v21
	v_mul_f32_e32 v28, 0xbfb8aa3b, v32
	v_mul_f32_e32 v29, 0xbfb8aa3b, v33
	v_mul_f32_e32 v30, 0xbfb8aa3b, v34
	v_mul_f32_e32 v31, 0xbfb8aa3b, v35
	v_exp_f32_e32 v28, v28
	v_exp_f32_e32 v29, v29
	v_exp_f32_e32 v30, v30
	v_exp_f32_e32 v31, v31
	v_add_f32_e32 v28, 1.0, v28
	v_add_f32_e32 v29, 1.0, v29
	v_add_f32_e32 v30, 1.0, v30
	v_add_f32_e32 v31, 1.0, v31
	v_rcp_f32_e32 v28, v28
	v_rcp_f32_e32 v29, v29
	v_rcp_f32_e32 v30, v30
	v_rcp_f32_e32 v31, v31
	v_pk_mul_f32 v[28:29], v[32:33], v[28:29]
	v_pk_mul_f32 v[30:31], v[34:35], v[30:31]
	v_pk_mul_f32 v[28:29], v[62:63], v[28:29]
	v_pk_mul_f32 v[30:31], v[64:65], v[30:31]
	v_cvt_pk_bf16_f32 v36, v28, v29
	v_cvt_pk_bf16_f32 v37, v30, v31
	global_store_dwordx2 v[4:5], v[36:37], off offset:320
	v_lshlrev_b32_e32 v32, 16, v22
	v_and_b32_e32 v33, 0xffff0000, v22
	v_lshlrev_b32_e32 v34, 16, v23
	v_and_b32_e32 v35, 0xffff0000, v23
	v_mul_f32_e32 v28, 0xbfb8aa3b, v32
	v_mul_f32_e32 v29, 0xbfb8aa3b, v33
	v_mul_f32_e32 v30, 0xbfb8aa3b, v34
	v_mul_f32_e32 v31, 0xbfb8aa3b, v35
	v_exp_f32_e32 v28, v28
	v_exp_f32_e32 v29, v29
	v_exp_f32_e32 v30, v30
	v_exp_f32_e32 v31, v31
	v_add_f32_e32 v28, 1.0, v28
	v_add_f32_e32 v29, 1.0, v29
	v_add_f32_e32 v30, 1.0, v30
	v_add_f32_e32 v31, 1.0, v31
	v_rcp_f32_e32 v28, v28
	v_rcp_f32_e32 v29, v29
	v_rcp_f32_e32 v30, v30
	v_rcp_f32_e32 v31, v31
	v_pk_mul_f32 v[28:29], v[32:33], v[28:29]
	v_pk_mul_f32 v[30:31], v[34:35], v[30:31]
	v_pk_mul_f32 v[28:29], v[66:67], v[28:29]
	v_pk_mul_f32 v[30:31], v[68:69], v[30:31]
	v_cvt_pk_bf16_f32 v38, v28, v29
	v_cvt_pk_bf16_f32 v39, v30, v31
	global_store_dwordx2 v[4:5], v[38:39], off offset:336
	v_lshlrev_b32_e32 v32, 16, v24
	v_and_b32_e32 v33, 0xffff0000, v24
	v_lshlrev_b32_e32 v34, 16, v25
	v_and_b32_e32 v35, 0xffff0000, v25
	v_mul_f32_e32 v28, 0xbfb8aa3b, v32
	v_mul_f32_e32 v29, 0xbfb8aa3b, v33
	v_mul_f32_e32 v30, 0xbfb8aa3b, v34
	v_mul_f32_e32 v31, 0xbfb8aa3b, v35
	v_exp_f32_e32 v28, v28
	v_exp_f32_e32 v29, v29
	v_exp_f32_e32 v30, v30
	v_exp_f32_e32 v31, v31
	v_add_f32_e32 v28, 1.0, v28
	v_add_f32_e32 v29, 1.0, v29
	v_add_f32_e32 v30, 1.0, v30
	v_add_f32_e32 v31, 1.0, v31
	v_rcp_f32_e32 v28, v28
	v_rcp_f32_e32 v29, v29
	v_rcp_f32_e32 v30, v30
	v_rcp_f32_e32 v31, v31
	v_pk_mul_f32 v[28:29], v[32:33], v[28:29]
	v_pk_mul_f32 v[30:31], v[34:35], v[30:31]
	v_pk_mul_f32 v[28:29], v[70:71], v[28:29]
	v_pk_mul_f32 v[30:31], v[72:73], v[30:31]
	v_cvt_pk_bf16_f32 v36, v28, v29
	v_cvt_pk_bf16_f32 v37, v30, v31
	global_store_dwordx2 v[4:5], v[36:37], off offset:352
	v_lshlrev_b32_e32 v32, 16, v26
	v_and_b32_e32 v33, 0xffff0000, v26
	v_lshlrev_b32_e32 v34, 16, v27
	v_and_b32_e32 v35, 0xffff0000, v27
	v_mul_f32_e32 v28, 0xbfb8aa3b, v32
	v_mul_f32_e32 v29, 0xbfb8aa3b, v33
	v_mul_f32_e32 v30, 0xbfb8aa3b, v34
	v_mul_f32_e32 v31, 0xbfb8aa3b, v35
	v_exp_f32_e32 v28, v28
	v_exp_f32_e32 v29, v29
	v_exp_f32_e32 v30, v30
	v_exp_f32_e32 v31, v31
	v_add_f32_e32 v28, 1.0, v28
	v_add_f32_e32 v29, 1.0, v29
	v_add_f32_e32 v30, 1.0, v30
	v_add_f32_e32 v31, 1.0, v31
	v_rcp_f32_e32 v28, v28
	v_rcp_f32_e32 v29, v29
	v_rcp_f32_e32 v30, v30
	v_rcp_f32_e32 v31, v31
	v_pk_mul_f32 v[28:29], v[32:33], v[28:29]
	v_pk_mul_f32 v[30:31], v[34:35], v[30:31]
	v_pk_mul_f32 v[28:29], v[74:75], v[28:29]
	v_pk_mul_f32 v[30:31], v[76:77], v[30:31]
	v_cvt_pk_bf16_f32 v38, v28, v29
	v_cvt_pk_bf16_f32 v39, v30, v31
	global_store_dwordx2 v[4:5], v[38:39], off offset:368
	v_readlane_b32 s54, v250, 29
	v_readlane_b32 s55, v250, 30
	v_mov_b32_e32 v2, v45
	v_mov_b32_e32 v3, 0
	s_nop 1
	v_lshl_add_u64 v[4:5], s[54:55], 0, v[2:3]
	global_load_dwordx4 v[12:15], v[4:5], off offset:-2048
	global_load_dwordx4 v[16:19], v[4:5], off offset:2048
	global_load_dwordx4 v[20:23], v[4:5], off offset:-2016
	global_load_dwordx4 v[24:27], v[4:5], off offset:2080
	global_load_dwordx4 v[28:31], v[4:5], off offset:-1984
	global_load_dwordx4 v[32:35], v[4:5], off offset:2112
	global_load_dwordx4 v[36:39], v[4:5], off offset:-1952
	global_load_dwordx4 v[40:43], v[4:5], off offset:2144
	ds_read_u16 v46, v8 offset:128
	ds_read_u16 v47, v8 offset:384
	ds_read_u16 v48, v8 offset:640
	ds_read_u16 v49, v8 offset:896
	ds_read_u16 v50, v8 offset:1152
	ds_read_u16 v51, v8 offset:1408
	ds_read_u16 v52, v8 offset:1664
	ds_read_u16 v53, v8 offset:1920
	ds_read_u16 v54, v8 offset:2176
	ds_read_u16 v55, v8 offset:2432
	ds_read_u16 v56, v8 offset:2688
	ds_read_u16 v57, v8 offset:2944
	ds_read_u16 v58, v8 offset:3200
	ds_read_u16 v59, v8 offset:3456
	ds_read_u16 v60, v8 offset:3712
	ds_read_u16 v61, v8 offset:3968
	ds_read_u16 v62, v8 offset:4224
	ds_read_u16 v63, v8 offset:4480
	ds_read_u16 v64, v8 offset:4736
	ds_read_u16 v65, v8 offset:4992
	ds_read_u16 v66, v8 offset:5248
	ds_read_u16 v67, v8 offset:5504
	ds_read_u16 v68, v8 offset:5760
	ds_read_u16 v69, v8 offset:6016
	ds_read_u16 v70, v8 offset:6272
	ds_read_u16 v71, v8 offset:6528
	ds_read_u16 v72, v8 offset:6784
	ds_read_u16 v73, v8 offset:7040
	ds_read_u16 v74, v8 offset:7296
	ds_read_u16 v75, v8 offset:7552
	ds_read_u16 v76, v8 offset:7808
	ds_read_u16 v77, v8 offset:8064
	ds_read_u16 v78, v8 offset:8320
	ds_read_u16 v79, v8 offset:8576
	ds_read_u16 v80, v8 offset:8832
	ds_read_u16 v81, v8 offset:9088
	ds_read_u16 v82, v8 offset:9344
	ds_read_u16 v83, v8 offset:9600
	ds_read_u16 v84, v8 offset:9856
	ds_read_u16 v85, v8 offset:10112
	ds_read_u16 v86, v8 offset:10368
	ds_read_u16 v87, v8 offset:10624
	ds_read_u16 v88, v8 offset:10880
	ds_read_u16 v89, v8 offset:11136
	ds_read_u16 v90, v8 offset:11392
	ds_read_u16 v91, v8 offset:11648
	ds_read_u16 v92, v8 offset:11904
	s_mov_b32 s50, 0x3d800000
	s_waitcnt lgkmcnt(0)
	v_lshlrev_b32_e32 v46, 16, v46
	v_lshlrev_b32_e32 v47, 16, v47
	v_lshlrev_b32_e32 v48, 16, v48
	v_lshlrev_b32_e32 v49, 16, v49
	v_lshlrev_b32_e32 v50, 16, v50
	v_lshlrev_b32_e32 v51, 16, v51
	v_lshlrev_b32_e32 v52, 16, v52
	v_lshlrev_b32_e32 v53, 16, v53
	v_lshlrev_b32_e32 v54, 16, v54
	v_lshlrev_b32_e32 v55, 16, v55
	v_lshlrev_b32_e32 v56, 16, v56
	v_lshlrev_b32_e32 v57, 16, v57
	v_lshlrev_b32_e32 v58, 16, v58
	v_lshlrev_b32_e32 v59, 16, v59
	v_lshlrev_b32_e32 v60, 16, v60
	v_lshlrev_b32_e32 v61, 16, v61
	v_lshlrev_b32_e32 v62, 16, v62
	v_lshlrev_b32_e32 v63, 16, v63
	v_lshlrev_b32_e32 v64, 16, v64
	v_lshlrev_b32_e32 v65, 16, v65
	v_lshlrev_b32_e32 v66, 16, v66
	v_lshlrev_b32_e32 v67, 16, v67
	v_lshlrev_b32_e32 v68, 16, v68
	v_lshlrev_b32_e32 v69, 16, v69
	v_lshlrev_b32_e32 v70, 16, v70
	v_lshlrev_b32_e32 v71, 16, v71
	v_lshlrev_b32_e32 v72, 16, v72
	v_lshlrev_b32_e32 v73, 16, v73
	v_lshlrev_b32_e32 v74, 16, v74
	v_lshlrev_b32_e32 v75, 16, v75
	v_lshlrev_b32_e32 v76, 16, v76
	v_lshlrev_b32_e32 v77, 16, v77
	v_lshlrev_b32_e32 v78, 16, v78
	v_lshlrev_b32_e32 v79, 16, v79
	v_lshlrev_b32_e32 v80, 16, v80
	v_lshlrev_b32_e32 v81, 16, v81
	v_lshlrev_b32_e32 v82, 16, v82
	v_lshlrev_b32_e32 v83, 16, v83
	v_lshlrev_b32_e32 v84, 16, v84
	v_lshlrev_b32_e32 v85, 16, v85
	v_lshlrev_b32_e32 v86, 16, v86
	v_lshlrev_b32_e32 v87, 16, v87
	v_lshlrev_b32_e32 v88, 16, v88
	v_lshlrev_b32_e32 v89, 16, v89
	v_lshlrev_b32_e32 v90, 16, v90
	v_lshlrev_b32_e32 v91, 16, v91
	v_lshlrev_b32_e32 v92, 16, v92
	s_cmp_eq_u32 s42, 1
	s_cbranch_scc0 .Lpool_nz3
	v_mov_b32_e32 v60, 0
	v_mov_b32_e32 v59, 0
	v_mov_b32_e32 v58, 0
	v_mov_b32_e32 v57, 0
	v_mov_b32_e32 v56, 0
	v_mov_b32_e32 v55, 0
	v_mov_b32_e32 v54, 0
	v_mov_b32_e32 v53, 0
	v_mov_b32_e32 v52, 0
	v_mov_b32_e32 v51, 0
	v_mov_b32_e32 v50, 0
	v_mov_b32_e32 v49, 0
	v_mov_b32_e32 v48, 0
	v_mov_b32_e32 v47, 0
	v_mov_b32_e32 v46, 0
.Lpool_nz3:
	v_add_f32_e32 v93, v61, v60
	v_add_f32_e32 v93, v93, v59
	v_add_f32_e32 v93, v93, v58
	v_add_f32_e32 v93, v93, v57
	v_add_f32_e32 v93, v93, v56
	v_add_f32_e32 v93, v93, v55
	v_add_f32_e32 v93, v93, v54
	v_add_f32_e32 v93, v93, v53
	v_add_f32_e32 v93, v93, v52
	v_add_f32_e32 v93, v93, v51
	v_add_f32_e32 v93, v93, v50
	v_add_f32_e32 v93, v93, v49
	v_add_f32_e32 v93, v93, v48
	v_add_f32_e32 v93, v93, v47
	v_add_f32_e32 v93, v93, v46
	s_cmp_eq_u32 s42, 1
	s_cselect_b32 s51, 0x3f800000, s50
	v_fma_f32 v2, v93, s51, -v61
	v_add_f32_e32 v93, v93, v62
	v_sub_f32_e32 v93, v93, v46
	s_cmp_eq_u32 s42, 1
	s_cselect_b32 s51, 0x3f000000, s50
	v_fma_f32 v3, v93, s51, -v62
	v_cvt_pk_bf16_f32 v2, v2, v3
	ds_write_b16 v9, v2 offset:0
	ds_write_b16_d16_hi v9, v2 offset:144
	v_add_f32_e32 v93, v93, v63
	v_sub_f32_e32 v93, v93, v47
	s_cmp_eq_u32 s42, 1
	s_cselect_b32 s51, 0x3eaaaaab, s50
	v_fma_f32 v4, v93, s51, -v63
	v_add_f32_e32 v93, v93, v64
	v_sub_f32_e32 v93, v93, v48
	s_cmp_eq_u32 s42, 1
	s_cselect_b32 s51, 0x3e800000, s50
	v_fma_f32 v5, v93, s51, -v64
	v_cvt_pk_bf16_f32 v4, v4, v5
	ds_write_b16 v9, v4 offset:288
	ds_write_b16_d16_hi v9, v4 offset:432
	v_add_f32_e32 v93, v93, v65
	v_sub_f32_e32 v93, v93, v49
	s_cmp_eq_u32 s42, 1
	s_cselect_b32 s51, 0x3e4ccccd, s50
	v_fma_f32 v2, v93, s51, -v65
	v_add_f32_e32 v93, v93, v66
	v_sub_f32_e32 v93, v93, v50
	s_cmp_eq_u32 s42, 1
	s_cselect_b32 s51, 0x3e2aaaab, s50
	v_fma_f32 v3, v93, s51, -v66
	v_cvt_pk_bf16_f32 v2, v2, v3
	ds_write_b16 v9, v2 offset:576
	ds_write_b16_d16_hi v9, v2 offset:720
	v_add_f32_e32 v93, v93, v67
	v_sub_f32_e32 v93, v93, v51
	s_cmp_eq_u32 s42, 1
	s_cselect_b32 s51, 0x3e124925, s50
	v_fma_f32 v4, v93, s51, -v67
	v_add_f32_e32 v93, v93, v68
	v_sub_f32_e32 v93, v93, v52
	s_cmp_eq_u32 s42, 1
	s_cselect_b32 s51, 0x3e000000, s50
	v_fma_f32 v5, v93, s51, -v68
	v_cvt_pk_bf16_f32 v4, v4, v5
	ds_write_b16 v9, v4 offset:864
	ds_write_b16_d16_hi v9, v4 offset:1008
	v_add_f32_e32 v93, v93, v69
	v_sub_f32_e32 v93, v93, v53
	s_cmp_eq_u32 s42, 1
	s_cselect_b32 s51, 0x3de38e39, s50
	v_fma_f32 v2, v93, s51, -v69
	v_add_f32_e32 v93, v93, v70
	v_sub_f32_e32 v93, v93, v54
	s_cmp_eq_u32 s42, 1
	s_cselect_b32 s51, 0x3dcccccd, s50
	v_fma_f32 v3, v93, s51, -v70
	v_cvt_pk_bf16_f32 v2, v2, v3
	ds_write_b16 v9, v2 offset:1152
	ds_write_b16_d16_hi v9, v2 offset:1296
	v_add_f32_e32 v93, v93, v71
	v_sub_f32_e32 v93, v93, v55
	s_cmp_eq_u32 s42, 1
	s_cselect_b32 s51, 0x3dba2e8c, s50
	v_fma_f32 v4, v93, s51, -v71
	v_add_f32_e32 v93, v93, v72
	v_sub_f32_e32 v93, v93, v56
	s_cmp_eq_u32 s42, 1
	s_cselect_b32 s51, 0x3daaaaab, s50
	v_fma_f32 v5, v93, s51, -v72
	v_cvt_pk_bf16_f32 v4, v4, v5
	ds_write_b16 v9, v4 offset:1440
	ds_write_b16_d16_hi v9, v4 offset:1584
	v_add_f32_e32 v93, v93, v73
	v_sub_f32_e32 v93, v93, v57
	s_cmp_eq_u32 s42, 1
	s_cselect_b32 s51, 0x3d9d89d9, s50
	v_fma_f32 v2, v93, s51, -v73
	v_add_f32_e32 v93, v93, v74
	v_sub_f32_e32 v93, v93, v58
	s_cmp_eq_u32 s42, 1
	s_cselect_b32 s51, 0x3d924925, s50
	v_fma_f32 v3, v93, s51, -v74
	v_cvt_pk_bf16_f32 v2, v2, v3
	ds_write_b16 v9, v2 offset:1728
	ds_write_b16_d16_hi v9, v2 offset:1872
	v_add_f32_e32 v93, v93, v75
	v_sub_f32_e32 v93, v93, v59
	s_cmp_eq_u32 s42, 1
	s_cselect_b32 s51, 0x3d888889, s50
	v_fma_f32 v4, v93, s51, -v75
	v_add_f32_e32 v93, v93, v76
	v_sub_f32_e32 v93, v93, v60
	v_fma_f32 v5, v93, s50, -v76
	v_cvt_pk_bf16_f32 v4, v4, v5
	ds_write_b16 v9, v4 offset:2016
	ds_write_b16_d16_hi v9, v4 offset:2160
	v_add_f32_e32 v93, v93, v77
	v_sub_f32_e32 v93, v93, v61
	v_fma_f32 v2, v93, s50, -v77
	v_add_f32_e32 v93, v93, v78
	v_sub_f32_e32 v93, v93, v62
	v_fma_f32 v3, v93, s50, -v78
	v_cvt_pk_bf16_f32 v2, v2, v3
	ds_write_b16 v9, v2 offset:2304
	ds_write_b16_d16_hi v9, v2 offset:2448
	v_add_f32_e32 v93, v93, v79
	v_sub_f32_e32 v93, v93, v63
	v_fma_f32 v4, v93, s50, -v79
	v_add_f32_e32 v93, v93, v80
	v_sub_f32_e32 v93, v93, v64
	v_fma_f32 v5, v93, s50, -v80
	v_cvt_pk_bf16_f32 v4, v4, v5
	ds_write_b16 v9, v4 offset:2592
	ds_write_b16_d16_hi v9, v4 offset:2736
	v_add_f32_e32 v93, v93, v81
	v_sub_f32_e32 v93, v93, v65
	v_fma_f32 v2, v93, s50, -v81
	v_add_f32_e32 v93, v93, v82
	v_sub_f32_e32 v93, v93, v66
	v_fma_f32 v3, v93, s50, -v82
	v_cvt_pk_bf16_f32 v2, v2, v3
	ds_write_b16 v9, v2 offset:2880
	ds_write_b16_d16_hi v9, v2 offset:3024
	v_add_f32_e32 v93, v93, v83
	v_sub_f32_e32 v93, v93, v67
	v_fma_f32 v4, v93, s50, -v83
	v_add_f32_e32 v93, v93, v84
	v_sub_f32_e32 v93, v93, v68
	v_fma_f32 v5, v93, s50, -v84
	v_cvt_pk_bf16_f32 v4, v4, v5
	ds_write_b16 v9, v4 offset:3168
	ds_write_b16_d16_hi v9, v4 offset:3312
	v_add_f32_e32 v93, v93, v85
	v_sub_f32_e32 v93, v93, v69
	v_fma_f32 v2, v93, s50, -v85
	v_add_f32_e32 v93, v93, v86
	v_sub_f32_e32 v93, v93, v70
	v_fma_f32 v3, v93, s50, -v86
	v_cvt_pk_bf16_f32 v2, v2, v3
	ds_write_b16 v9, v2 offset:3456
	ds_write_b16_d16_hi v9, v2 offset:3600
	v_add_f32_e32 v93, v93, v87
	v_sub_f32_e32 v93, v93, v71
	v_fma_f32 v4, v93, s50, -v87
	v_add_f32_e32 v93, v93, v88
	v_sub_f32_e32 v93, v93, v72
	v_fma_f32 v5, v93, s50, -v88
	v_cvt_pk_bf16_f32 v4, v4, v5
	ds_write_b16 v9, v4 offset:3744
	ds_write_b16_d16_hi v9, v4 offset:3888
	v_add_f32_e32 v93, v93, v89
	v_sub_f32_e32 v93, v93, v73
	v_fma_f32 v2, v93, s50, -v89
	v_add_f32_e32 v93, v93, v90
	v_sub_f32_e32 v93, v93, v74
	v_fma_f32 v3, v93, s50, -v90
	v_cvt_pk_bf16_f32 v2, v2, v3
	ds_write_b16 v9, v2 offset:4032
	ds_write_b16_d16_hi v9, v2 offset:4176
	v_add_f32_e32 v93, v93, v91
	v_sub_f32_e32 v93, v93, v75
	v_fma_f32 v4, v93, s50, -v91
	v_add_f32_e32 v93, v93, v92
	v_sub_f32_e32 v93, v93, v76
	v_fma_f32 v5, v93, s50, -v92
	v_cvt_pk_bf16_f32 v4, v4, v5
	ds_write_b16 v9, v4 offset:4320
	ds_write_b16_d16_hi v9, v4 offset:4464
	s_waitcnt lgkmcnt(0)
	ds_read_b128 v[78:81], v44 offset:0
	ds_read_b128 v[82:85], v44 offset:32
	ds_read_b128 v[86:89], v44 offset:64
	ds_read_b128 v[90:93], v44 offset:96
	v_lshl_add_u64 v[4:5], s[52:53], 0, v[10:11]
	s_waitcnt vmcnt(0)
	s_waitcnt lgkmcnt(0)
	v_mfma_f32_32x32x16_bf16 v[46:61], v[12:15], v[78:81], 0
	v_mfma_f32_32x32x16_bf16 v[62:77], v[16:19], v[78:81], 0
	global_load_dwordx2 v[12:13], v[4:5], off offset:384
	global_load_dwordx2 v[14:15], v[4:5], off offset:400
	global_load_dwordx2 v[16:17], v[4:5], off offset:416
	global_load_dwordx2 v[18:19], v[4:5], off offset:432
	v_mfma_f32_32x32x16_bf16 v[46:61], v[20:23], v[82:85], v[46:61]
	v_mfma_f32_32x32x16_bf16 v[62:77], v[24:27], v[82:85], v[62:77]
	global_load_dwordx2 v[20:21], v[4:5], off offset:448
	global_load_dwordx2 v[22:23], v[4:5], off offset:464
	global_load_dwordx2 v[24:25], v[4:5], off offset:480
	global_load_dwordx2 v[26:27], v[4:5], off offset:496
	v_mfma_f32_32x32x16_bf16 v[46:61], v[28:31], v[86:89], v[46:61]
	v_mfma_f32_32x32x16_bf16 v[62:77], v[32:35], v[86:89], v[62:77]
	v_mfma_f32_32x32x16_bf16 v[46:61], v[36:39], v[90:93], v[46:61]
	v_mfma_f32_32x32x16_bf16 v[62:77], v[40:43], v[90:93], v[62:77]
	s_nop 15
	s_waitcnt vmcnt(0)
	v_lshlrev_b32_e32 v32, 16, v12
	v_and_b32_e32 v33, 0xffff0000, v12
	v_lshlrev_b32_e32 v34, 16, v13
	v_and_b32_e32 v35, 0xffff0000, v13
	v_mul_f32_e32 v28, 0xbfb8aa3b, v32
	v_mul_f32_e32 v29, 0xbfb8aa3b, v33
	v_mul_f32_e32 v30, 0xbfb8aa3b, v34
	v_mul_f32_e32 v31, 0xbfb8aa3b, v35
	v_exp_f32_e32 v28, v28
	v_exp_f32_e32 v29, v29
	v_exp_f32_e32 v30, v30
	v_exp_f32_e32 v31, v31
	v_add_f32_e32 v28, 1.0, v28
	v_add_f32_e32 v29, 1.0, v29
	v_add_f32_e32 v30, 1.0, v30
	v_add_f32_e32 v31, 1.0, v31
	v_rcp_f32_e32 v28, v28
	v_rcp_f32_e32 v29, v29
	v_rcp_f32_e32 v30, v30
	v_rcp_f32_e32 v31, v31
	v_pk_mul_f32 v[28:29], v[32:33], v[28:29]
	v_pk_mul_f32 v[30:31], v[34:35], v[30:31]
	v_pk_mul_f32 v[28:29], v[46:47], v[28:29]
	v_pk_mul_f32 v[30:31], v[48:49], v[30:31]
	v_cvt_pk_bf16_f32 v36, v28, v29
	v_cvt_pk_bf16_f32 v37, v30, v31
	global_store_dwordx2 v[4:5], v[36:37], off offset:384
	v_lshlrev_b32_e32 v32, 16, v14
	v_and_b32_e32 v33, 0xffff0000, v14
	v_lshlrev_b32_e32 v34, 16, v15
	v_and_b32_e32 v35, 0xffff0000, v15
	v_mul_f32_e32 v28, 0xbfb8aa3b, v32
	v_mul_f32_e32 v29, 0xbfb8aa3b, v33
	v_mul_f32_e32 v30, 0xbfb8aa3b, v34
	v_mul_f32_e32 v31, 0xbfb8aa3b, v35
	v_exp_f32_e32 v28, v28
	v_exp_f32_e32 v29, v29
	v_exp_f32_e32 v30, v30
	v_exp_f32_e32 v31, v31
	v_add_f32_e32 v28, 1.0, v28
	v_add_f32_e32 v29, 1.0, v29
	v_add_f32_e32 v30, 1.0, v30
	v_add_f32_e32 v31, 1.0, v31
	v_rcp_f32_e32 v28, v28
	v_rcp_f32_e32 v29, v29
	v_rcp_f32_e32 v30, v30
	v_rcp_f32_e32 v31, v31
	v_pk_mul_f32 v[28:29], v[32:33], v[28:29]
	v_pk_mul_f32 v[30:31], v[34:35], v[30:31]
	v_pk_mul_f32 v[28:29], v[50:51], v[28:29]
	v_pk_mul_f32 v[30:31], v[52:53], v[30:31]
	v_cvt_pk_bf16_f32 v38, v28, v29
	v_cvt_pk_bf16_f32 v39, v30, v31
	global_store_dwordx2 v[4:5], v[38:39], off offset:400
	v_lshlrev_b32_e32 v32, 16, v16
	v_and_b32_e32 v33, 0xffff0000, v16
	v_lshlrev_b32_e32 v34, 16, v17
	v_and_b32_e32 v35, 0xffff0000, v17
	v_mul_f32_e32 v28, 0xbfb8aa3b, v32
	v_mul_f32_e32 v29, 0xbfb8aa3b, v33
	v_mul_f32_e32 v30, 0xbfb8aa3b, v34
	v_mul_f32_e32 v31, 0xbfb8aa3b, v35
	v_exp_f32_e32 v28, v28
	v_exp_f32_e32 v29, v29
	v_exp_f32_e32 v30, v30
	v_exp_f32_e32 v31, v31
	v_add_f32_e32 v28, 1.0, v28
	v_add_f32_e32 v29, 1.0, v29
	v_add_f32_e32 v30, 1.0, v30
	v_add_f32_e32 v31, 1.0, v31
	v_rcp_f32_e32 v28, v28
	v_rcp_f32_e32 v29, v29
	v_rcp_f32_e32 v30, v30
	v_rcp_f32_e32 v31, v31
	v_pk_mul_f32 v[28:29], v[32:33], v[28:29]
	v_pk_mul_f32 v[30:31], v[34:35], v[30:31]
	v_pk_mul_f32 v[28:29], v[54:55], v[28:29]
	v_pk_mul_f32 v[30:31], v[56:57], v[30:31]
	v_cvt_pk_bf16_f32 v36, v28, v29
	v_cvt_pk_bf16_f32 v37, v30, v31
	global_store_dwordx2 v[4:5], v[36:37], off offset:416
	v_lshlrev_b32_e32 v32, 16, v18
	v_and_b32_e32 v33, 0xffff0000, v18
	v_lshlrev_b32_e32 v34, 16, v19
	v_and_b32_e32 v35, 0xffff0000, v19
	v_mul_f32_e32 v28, 0xbfb8aa3b, v32
	v_mul_f32_e32 v29, 0xbfb8aa3b, v33
	v_mul_f32_e32 v30, 0xbfb8aa3b, v34
	v_mul_f32_e32 v31, 0xbfb8aa3b, v35
	v_exp_f32_e32 v28, v28
	v_exp_f32_e32 v29, v29
	v_exp_f32_e32 v30, v30
	v_exp_f32_e32 v31, v31
	v_add_f32_e32 v28, 1.0, v28
	v_add_f32_e32 v29, 1.0, v29
	v_add_f32_e32 v30, 1.0, v30
	v_add_f32_e32 v31, 1.0, v31
	v_rcp_f32_e32 v28, v28
	v_rcp_f32_e32 v29, v29
	v_rcp_f32_e32 v30, v30
	v_rcp_f32_e32 v31, v31
	v_pk_mul_f32 v[28:29], v[32:33], v[28:29]
	v_pk_mul_f32 v[30:31], v[34:35], v[30:31]
	v_pk_mul_f32 v[28:29], v[58:59], v[28:29]
	v_pk_mul_f32 v[30:31], v[60:61], v[30:31]
	v_cvt_pk_bf16_f32 v38, v28, v29
	v_cvt_pk_bf16_f32 v39, v30, v31
	global_store_dwordx2 v[4:5], v[38:39], off offset:432
	v_lshlrev_b32_e32 v32, 16, v20
	v_and_b32_e32 v33, 0xffff0000, v20
	v_lshlrev_b32_e32 v34, 16, v21
	v_and_b32_e32 v35, 0xffff0000, v21
	v_mul_f32_e32 v28, 0xbfb8aa3b, v32
	v_mul_f32_e32 v29, 0xbfb8aa3b, v33
	v_mul_f32_e32 v30, 0xbfb8aa3b, v34
	v_mul_f32_e32 v31, 0xbfb8aa3b, v35
	v_exp_f32_e32 v28, v28
	v_exp_f32_e32 v29, v29
	v_exp_f32_e32 v30, v30
	v_exp_f32_e32 v31, v31
	v_add_f32_e32 v28, 1.0, v28
	v_add_f32_e32 v29, 1.0, v29
	v_add_f32_e32 v30, 1.0, v30
	v_add_f32_e32 v31, 1.0, v31
	v_rcp_f32_e32 v28, v28
	v_rcp_f32_e32 v29, v29
	v_rcp_f32_e32 v30, v30
	v_rcp_f32_e32 v31, v31
	v_pk_mul_f32 v[28:29], v[32:33], v[28:29]
	v_pk_mul_f32 v[30:31], v[34:35], v[30:31]
	v_pk_mul_f32 v[28:29], v[62:63], v[28:29]
	v_pk_mul_f32 v[30:31], v[64:65], v[30:31]
	v_cvt_pk_bf16_f32 v36, v28, v29
	v_cvt_pk_bf16_f32 v37, v30, v31
	global_store_dwordx2 v[4:5], v[36:37], off offset:448
	v_lshlrev_b32_e32 v32, 16, v22
	v_and_b32_e32 v33, 0xffff0000, v22
	v_lshlrev_b32_e32 v34, 16, v23
	v_and_b32_e32 v35, 0xffff0000, v23
	v_mul_f32_e32 v28, 0xbfb8aa3b, v32
	v_mul_f32_e32 v29, 0xbfb8aa3b, v33
	v_mul_f32_e32 v30, 0xbfb8aa3b, v34
	v_mul_f32_e32 v31, 0xbfb8aa3b, v35
	v_exp_f32_e32 v28, v28
	v_exp_f32_e32 v29, v29
	v_exp_f32_e32 v30, v30
	v_exp_f32_e32 v31, v31
	v_add_f32_e32 v28, 1.0, v28
	v_add_f32_e32 v29, 1.0, v29
	v_add_f32_e32 v30, 1.0, v30
	v_add_f32_e32 v31, 1.0, v31
	v_rcp_f32_e32 v28, v28
	v_rcp_f32_e32 v29, v29
	v_rcp_f32_e32 v30, v30
	v_rcp_f32_e32 v31, v31
	v_pk_mul_f32 v[28:29], v[32:33], v[28:29]
	v_pk_mul_f32 v[30:31], v[34:35], v[30:31]
	v_pk_mul_f32 v[28:29], v[66:67], v[28:29]
	v_pk_mul_f32 v[30:31], v[68:69], v[30:31]
	v_cvt_pk_bf16_f32 v38, v28, v29
	v_cvt_pk_bf16_f32 v39, v30, v31
	global_store_dwordx2 v[4:5], v[38:39], off offset:464
	v_lshlrev_b32_e32 v32, 16, v24
	v_and_b32_e32 v33, 0xffff0000, v24
	v_lshlrev_b32_e32 v34, 16, v25
	v_and_b32_e32 v35, 0xffff0000, v25
	v_mul_f32_e32 v28, 0xbfb8aa3b, v32
	v_mul_f32_e32 v29, 0xbfb8aa3b, v33
	v_mul_f32_e32 v30, 0xbfb8aa3b, v34
	v_mul_f32_e32 v31, 0xbfb8aa3b, v35
	v_exp_f32_e32 v28, v28
	v_exp_f32_e32 v29, v29
	v_exp_f32_e32 v30, v30
	v_exp_f32_e32 v31, v31
	v_add_f32_e32 v28, 1.0, v28
	v_add_f32_e32 v29, 1.0, v29
	v_add_f32_e32 v30, 1.0, v30
	v_add_f32_e32 v31, 1.0, v31
	v_rcp_f32_e32 v28, v28
	v_rcp_f32_e32 v29, v29
	v_rcp_f32_e32 v30, v30
	v_rcp_f32_e32 v31, v31
	v_pk_mul_f32 v[28:29], v[32:33], v[28:29]
	v_pk_mul_f32 v[30:31], v[34:35], v[30:31]
	v_pk_mul_f32 v[28:29], v[70:71], v[28:29]
	v_pk_mul_f32 v[30:31], v[72:73], v[30:31]
	v_cvt_pk_bf16_f32 v36, v28, v29
	v_cvt_pk_bf16_f32 v37, v30, v31
	global_store_dwordx2 v[4:5], v[36:37], off offset:480
	v_lshlrev_b32_e32 v32, 16, v26
	v_and_b32_e32 v33, 0xffff0000, v26
	v_lshlrev_b32_e32 v34, 16, v27
	v_and_b32_e32 v35, 0xffff0000, v27
	v_mul_f32_e32 v28, 0xbfb8aa3b, v32
	v_mul_f32_e32 v29, 0xbfb8aa3b, v33
	v_mul_f32_e32 v30, 0xbfb8aa3b, v34
	v_mul_f32_e32 v31, 0xbfb8aa3b, v35
	v_exp_f32_e32 v28, v28
	v_exp_f32_e32 v29, v29
	v_exp_f32_e32 v30, v30
	v_exp_f32_e32 v31, v31
	v_add_f32_e32 v28, 1.0, v28
	v_add_f32_e32 v29, 1.0, v29
	v_add_f32_e32 v30, 1.0, v30
	v_add_f32_e32 v31, 1.0, v31
	v_rcp_f32_e32 v28, v28
	v_rcp_f32_e32 v29, v29
	v_rcp_f32_e32 v30, v30
	v_rcp_f32_e32 v31, v31
	v_pk_mul_f32 v[28:29], v[32:33], v[28:29]
	v_pk_mul_f32 v[30:31], v[34:35], v[30:31]
	v_pk_mul_f32 v[28:29], v[74:75], v[28:29]
	v_pk_mul_f32 v[30:31], v[76:77], v[30:31]
	v_cvt_pk_bf16_f32 v38, v28, v29
	v_cvt_pk_bf16_f32 v39, v30, v31
	global_store_dwordx2 v[4:5], v[38:39], off offset:496
	s_mov_b32 m0, s59
	v_readlane_b32 s38, v250, 39
	v_readlane_b32 s39, v250, 40
	s_barrier
